# strategy 4: static s_setprio 1 for waves 4-7 per GEMM phase (4 store GEMMs + phase 5), per-segment setprio flips deleted
# speedup vs baseline: 1.0066x; 1.0044x over previous
; #define GSYNC() xcd_barrier(xb)
; #define SEAM(k) do { if (IN(k) && IN((k) + 1)) GSYNC(); } while (0)
; __device__ __forceinline__ void run_gemm_store(const Params& p, LAS unsigned char* ldsl, const int ph) {
;     ...
;     pg8::Gemm g{D}; pg8::SegOrder S; S.init(D, gridDim.x, blockIdx.x);
;     pg8::EpiBf16 E{(bf16_t*)(ws + WS_P), NIN, (bf16_t*)(ws + WS_VT), MALL, 0};
;     if (ph == 2) { S.add(A, ws + WS_WIN, MALL / 256, NIN / 256, 1, D / 64, 0); S.add(ws + WS_WV0, A, 1024 / 256, MALL / 256, 1, D / 64, 1); }
; __global__ void __launch_bounds__(512, 2) fwd_megakernel(Params p) {
;     ...
;     if (IN(2)) { for (int rep_ = 0; rep_ < NREP(2); ++rep_) { if (rep_) GSYNC(); if (PH(2)) run_gemm_store(p, ldsl, 2); } } SEAM(2);
.LBB0_198:
	s_cmp_lt_i32 s80, 3
	s_cselect_b64 s[2:3], -1, 0
	s_and_b64 s[0:1], s[2:3], s[0:1]
	s_andn2_b64 vcc, exec, s[0:1]
	s_cbranch_vccnz .LBB0_227
	v_readfirstlane_b32 s101, v162
	s_nop 3
	s_lshr_b32 s101, s101, 6
	s_cmp_ge_u32 s101, 4
	s_cbranch_scc0 .Lsp_4258
	s_setprio 1
.Lsp_4258:
	s_ashr_i32 s30, s92, 31
	s_cmpk_lt_i32 s92, 0x484
	s_cselect_b64 s[8:9], -1, 0
	v_readfirstlane_b32 s10, v162
	s_and_b64 vcc, exec, s[8:9]
	s_cbranch_vccnz .LBB0_201
	s_add_u32 s6, s92, 0xfffffb7c
	s_addc_u32 s7, s30, -1
	v_mov_b64_e32 v[0:1], 0x110
	v_cmp_lt_u64_e64 s[8:9], s[6:7], v[0:1]
	s_mov_b32 s34, 1
	s_movk_i32 s13, 0x44
	s_mov_b32 s12, 4
	s_mov_b64 s[4:5], 0xc600000
	s_mov_b64 s[2:3], 0x1200000
	s_andn2_b64 vcc, exec, s[8:9]
	s_cbranch_vccz .LBB0_202
	s_branch .LBB0_227

; #define PG8_STAGE(bufoff, gbase, voff) do { _Pragma("unroll") for (int _i = 0; _i < 2; ++_i) \
;         __builtin_amdgcn_global_load_lds((const unsigned*)((const char*)(gbase) + (voff)[_i]), (LAS unsigned*)(lds + (bufoff) + ldsw + _i * 8192), 16, 0, 0); } while (0)
; #define PG8_LDA(dst, b, h) do { _Pragma("unroll") for (int m = 0; m < 4; ++m) _Pragma("unroll") for (int k = 0; k < 2; ++k) dst[m][k] = *(const LAS bf16x8*)(lds + PG8_SA(b, h) + aoff + m * 2048 + k * 1024); } while (0)
; #define PG8_LDB(dst, b, h) do { _Pragma("unroll") for (int n = 0; n < 2; ++n) _Pragma("unroll") for (int k = 0; k < 2; ++k) dst[n][k] = *(const LAS bf16x8*)(lds + PG8_SB(b, h) + boff + n * 2048 + k * 1024); } while (0)
; #define PG8_MMA(ai, bj, At, Bt) do { __builtin_amdgcn_s_setprio(1); _Pragma("unroll") for (int m = 0; m < 4; ++m) _Pragma("unroll") for (int n = 0; n < 2; ++n) _Pragma("unroll") for (int k = 0; k < 2; ++k) \
;         acc[ai][bj][m][n] = __builtin_amdgcn_mfma_f32_16x16x32_bf16(Bt[n][k], At[m][k], acc[ai][bj][m][n], 0, 0, 0); __builtin_amdgcn_s_setprio(0); } while (0)
; #define PG8_WAIT_V(n) asm volatile("s_waitcnt vmcnt(" #n ")" ::: "memory")
; #define PG8_WAIT_L(n) asm volatile("s_waitcnt lgkmcnt(" #n ")" ::: "memory")
; #define PG8_BAR __builtin_amdgcn_s_barrier()
; #define PG8_SCHED __builtin_amdgcn_sched_barrier(0)
; template <class Epi, class Sched, bool ALIGN_EPI = false, bool SP2 = false>
; __device__ __forceinline__ void gemm_phase(LAS unsigned char* lds, const Gemm g, const Sched& S, const Epi& E) {
;     ...
;             PG8_LDB(B0, 0, 0); PG8_LDB(B1, 0, 1); PG8_SCHED; PG8_LDA(At, 0, 0); PG8_STAGE(PG8_SA(1, 1), a1 + hstep, voffA);
;             PG8_WAIT_V(8); PG8_WAIT_L(0); PG8_BAR; PG8_MMA(0, 0, At, B0); PG8_MMA(0, 1, At, B1); PG8_BAR; PG8_SCHED;
;             PG8_LDA(At, 0, 1); PG8_STAGE(PG8_SB(0, 0), b2, voffB); PG8_STAGE(PG8_SB(0, 1), b2 + hstep, voffB); PG8_STAGE(PG8_SA(0, 0), a2, voffA);
;             PG8_WAIT_V(8); PG8_WAIT_L(0); PG8_BAR; PG8_MMA(1, 0, At, B0); PG8_MMA(1, 1, At, B1); PG8_BAR; PG8_SCHED;
.LBB0_220:
	ds_read_b128 v[152:155], v148
	ds_read_b128 v[156:159], v148 offset:1024
	ds_read_b128 v[164:167], v148 offset:2048
	ds_read_b128 v[170:173], v148 offset:3072
	ds_read_b128 v[174:177], v149
	ds_read_b128 v[178:181], v149 offset:1024
	ds_read_b128 v[182:185], v149 offset:2048
	ds_read_b128 v[186:189], v149 offset:3072
	s_add_u32 s22, s20, 0xfff80080
	s_addc_u32 s23, s21, -1
	s_cmp_eq_u32 s70, 28
	s_cselect_b32 s25, s13, s23
	s_cselect_b32 s24, s26, s22
	s_cselect_b32 s23, s27, s69
	s_cselect_b32 s22, s28, s29
	v_lshl_add_u64 v[222:223], s[20:21], 0, v[136:137]
	s_add_i32 m0, s33, 0xc000
	ds_read_b128 v[190:193], v150
	ds_read_b128 v[194:197], v150 offset:1024
	ds_read_b128 v[198:201], v150 offset:2048
	ds_read_b128 v[202:205], v150 offset:3072
	ds_read_b128 v[206:209], v150 offset:4096
	ds_read_b128 v[210:213], v150 offset:5120
	ds_read_b128 v[214:217], v150 offset:6144
	ds_read_b128 v[218:221], v150 offset:7168
	global_load_lds_dwordx4 v[222:223], off
	v_lshl_add_u64 v[222:223], s[20:21], 0, v[138:139]
	s_add_i32 m0, s33, 0xe000
	s_nop 0
	global_load_lds_dwordx4 v[222:223], off
	s_waitcnt vmcnt(8)
	s_waitcnt lgkmcnt(0)
	s_barrier
	s_waitcnt lgkmcnt(0)
	v_mfma_f32_16x16x32_bf16 v[124:127], v[152:155], v[190:193], v[124:127]
	v_mfma_f32_16x16x32_bf16 v[120:123], v[164:167], v[190:193], v[120:123]
	v_mfma_f32_16x16x32_bf16 v[116:119], v[152:155], v[198:201], v[116:119]
	v_mfma_f32_16x16x32_bf16 v[112:115], v[164:167], v[198:201], v[112:115]
	v_mfma_f32_16x16x32_bf16 v[100:103], v[152:155], v[206:209], v[100:103]
	v_mfma_f32_16x16x32_bf16 v[96:99], v[164:167], v[206:209], v[96:99]
	v_mfma_f32_16x16x32_bf16 v[84:87], v[152:155], v[214:217], v[84:87]
	v_mfma_f32_16x16x32_bf16 v[80:83], v[164:167], v[214:217], v[80:83]
	v_mfma_f32_16x16x32_bf16 v[124:127], v[156:159], v[194:197], v[124:127]
	v_mfma_f32_16x16x32_bf16 v[120:123], v[170:173], v[194:197], v[120:123]
	v_mfma_f32_16x16x32_bf16 v[116:119], v[156:159], v[202:205], v[116:119]
	v_mfma_f32_16x16x32_bf16 v[112:115], v[170:173], v[202:205], v[112:115]
	v_mfma_f32_16x16x32_bf16 v[100:103], v[156:159], v[210:213], v[100:103]
	v_mfma_f32_16x16x32_bf16 v[96:99], v[170:173], v[210:213], v[96:99]
	v_mfma_f32_16x16x32_bf16 v[84:87], v[156:159], v[218:221], v[84:87]
	v_mfma_f32_16x16x32_bf16 v[80:83], v[170:173], v[218:221], v[80:83]
	v_mfma_f32_16x16x32_bf16 v[108:111], v[174:177], v[190:193], v[108:111]
	v_mfma_f32_16x16x32_bf16 v[104:107], v[182:185], v[190:193], v[104:107]
	v_mfma_f32_16x16x32_bf16 v[92:95], v[174:177], v[198:201], v[92:95]
	v_mfma_f32_16x16x32_bf16 v[88:91], v[182:185], v[198:201], v[88:91]
	v_mfma_f32_16x16x32_bf16 v[76:79], v[174:177], v[206:209], v[76:79]
	v_mfma_f32_16x16x32_bf16 v[72:75], v[182:185], v[206:209], v[72:75]
	v_mfma_f32_16x16x32_bf16 v[68:71], v[174:177], v[214:217], v[68:71]
	v_mfma_f32_16x16x32_bf16 v[64:67], v[182:185], v[214:217], v[64:67]
	v_mfma_f32_16x16x32_bf16 v[108:111], v[178:181], v[194:197], v[108:111]
	v_mfma_f32_16x16x32_bf16 v[104:107], v[186:189], v[194:197], v[104:107]
	v_mfma_f32_16x16x32_bf16 v[92:95], v[178:181], v[202:205], v[92:95]
	v_mfma_f32_16x16x32_bf16 v[88:91], v[186:189], v[202:205], v[88:91]
	v_mfma_f32_16x16x32_bf16 v[76:79], v[178:181], v[210:213], v[76:79]
	v_mfma_f32_16x16x32_bf16 v[72:75], v[186:189], v[210:213], v[72:75]
	v_mfma_f32_16x16x32_bf16 v[68:71], v[178:181], v[218:221], v[68:71]
	v_mfma_f32_16x16x32_bf16 v[64:67], v[186:189], v[218:221], v[64:67]
	s_barrier
	s_add_i32 s71, s59, s31
	v_lshl_add_u64 v[222:223], s[22:23], 0, v[130:131]
	s_mov_b32 m0, s71
	ds_read_b128 v[190:193], v150 offset:16384
	ds_read_b128 v[194:197], v150 offset:17408
	ds_read_b128 v[198:201], v150 offset:18432
	ds_read_b128 v[202:205], v150 offset:19456
	ds_read_b128 v[206:209], v150 offset:20480
	ds_read_b128 v[210:213], v150 offset:21504
	ds_read_b128 v[214:217], v150 offset:22528
	ds_read_b128 v[218:221], v150 offset:23552
	global_load_lds_dwordx4 v[222:223], off
	s_add_i32 m0, s71, 0x2000
	s_add_u32 s72, s22, 0x80000
	v_lshl_add_u64 v[224:225], s[22:23], 0, v[134:135]
	s_addc_u32 s73, s23, 0
	s_add_i32 s71, s68, s31
	global_load_lds_dwordx4 v[224:225], off
	v_lshl_add_u64 v[226:227], s[72:73], 0, v[130:131]
	s_mov_b32 m0, s71
	v_lshl_add_u64 v[228:229], s[24:25], 0, v[132:133]
	global_load_lds_dwordx4 v[226:227], off
	v_lshl_add_u64 v[226:227], s[72:73], 0, v[134:135]
	s_add_i32 m0, s71, 0x2000
	s_nop 0
	global_load_lds_dwordx4 v[226:227], off
	v_lshl_add_u64 v[226:227], s[24:25], 0, v[128:129]
	s_mov_b32 m0, s33
	s_nop 0
	global_load_lds_dwordx4 v[226:227], off
	s_mov_b32 m0, s35
	s_nop 0
	global_load_lds_dwordx4 v[228:229], off
	s_waitcnt vmcnt(8)
	s_waitcnt lgkmcnt(0)
	s_barrier
; #define PG8_STAGE(bufoff, gbase, voff) do { _Pragma("unroll") for (int _i = 0; _i < 2; ++_i) \
;         __builtin_amdgcn_global_load_lds((const unsigned*)((const char*)(gbase) + (voff)[_i]), (LAS unsigned*)(lds + (bufoff) + ldsw + _i * 8192), 16, 0, 0); } while (0)
; #define PG8_LDA(dst, b, h) do { _Pragma("unroll") for (int m = 0; m < 4; ++m) _Pragma("unroll") for (int k = 0; k < 2; ++k) dst[m][k] = *(const LAS bf16x8*)(lds + PG8_SA(b, h) + aoff + m * 2048 + k * 1024); } while (0)
; #define PG8_LDB(dst, b, h) do { _Pragma("unroll") for (int n = 0; n < 2; ++n) _Pragma("unroll") for (int k = 0; k < 2; ++k) dst[n][k] = *(const LAS bf16x8*)(lds + PG8_SB(b, h) + boff + n * 2048 + k * 1024); } while (0)
; #define PG8_MMA(ai, bj, At, Bt) do { __builtin_amdgcn_s_setprio(1); _Pragma("unroll") for (int m = 0; m < 4; ++m) _Pragma("unroll") for (int n = 0; n < 2; ++n) _Pragma("unroll") for (int k = 0; k < 2; ++k) \
;         acc[ai][bj][m][n] = __builtin_amdgcn_mfma_f32_16x16x32_bf16(Bt[n][k], At[m][k], acc[ai][bj][m][n], 0, 0, 0); __builtin_amdgcn_s_setprio(0); } while (0)
; #define PG8_WAIT_V(n) asm volatile("s_waitcnt vmcnt(" #n ")" ::: "memory")
; #define PG8_WAIT_L(n) asm volatile("s_waitcnt lgkmcnt(" #n ")" ::: "memory")
; #define PG8_BAR __builtin_amdgcn_s_barrier()
; #define PG8_SCHED __builtin_amdgcn_sched_barrier(0)
; template <class Epi, class Sched, bool ALIGN_EPI = false, bool SP2 = false>
; __device__ __forceinline__ void gemm_phase(LAS unsigned char* lds, const Gemm g, const Sched& S, const Epi& E) {
;     ...
;             PG8_WAIT_V(8); PG8_WAIT_L(0); PG8_BAR; PG8_MMA(1, 0, At, B0); PG8_MMA(1, 1, At, B1); PG8_BAR; PG8_SCHED;
;             PG8_LDB(B0, 1, 0); PG8_LDB(B1, 1, 1); PG8_SCHED; PG8_LDA(At, 1, 0); PG8_STAGE(PG8_SA(0, 1), a2 + hstep, voffA);
;             PG8_WAIT_V(8); PG8_WAIT_L(0); PG8_BAR; PG8_MMA(0, 0, At, B0); PG8_MMA(0, 1, At, B1); PG8_BAR; PG8_SCHED;
	s_waitcnt lgkmcnt(0)
	v_mfma_f32_16x16x32_bf16 v[60:63], v[152:155], v[190:193], v[60:63]
	v_mfma_f32_16x16x32_bf16 v[56:59], v[164:167], v[190:193], v[56:59]
	v_mfma_f32_16x16x32_bf16 v[52:55], v[152:155], v[198:201], v[52:55]
	v_mfma_f32_16x16x32_bf16 v[48:51], v[164:167], v[198:201], v[48:51]
	v_mfma_f32_16x16x32_bf16 v[36:39], v[152:155], v[206:209], v[36:39]
	v_mfma_f32_16x16x32_bf16 v[32:35], v[164:167], v[206:209], v[32:35]
	v_mfma_f32_16x16x32_bf16 v[20:23], v[152:155], v[214:217], v[20:23]
	v_mfma_f32_16x16x32_bf16 v[16:19], v[164:167], v[214:217], v[16:19]
	v_mfma_f32_16x16x32_bf16 v[60:63], v[156:159], v[194:197], v[60:63]
	v_mfma_f32_16x16x32_bf16 v[56:59], v[170:173], v[194:197], v[56:59]
	v_mfma_f32_16x16x32_bf16 v[52:55], v[156:159], v[202:205], v[52:55]
	v_mfma_f32_16x16x32_bf16 v[48:51], v[170:173], v[202:205], v[48:51]
	v_mfma_f32_16x16x32_bf16 v[36:39], v[156:159], v[210:213], v[36:39]
	v_mfma_f32_16x16x32_bf16 v[32:35], v[170:173], v[210:213], v[32:35]
	v_mfma_f32_16x16x32_bf16 v[20:23], v[156:159], v[218:221], v[20:23]
	v_mfma_f32_16x16x32_bf16 v[16:19], v[170:173], v[218:221], v[16:19]
	v_mfma_f32_16x16x32_bf16 v[44:47], v[174:177], v[190:193], v[44:47]
	v_mfma_f32_16x16x32_bf16 v[40:43], v[182:185], v[190:193], v[40:43]
	v_mfma_f32_16x16x32_bf16 v[28:31], v[174:177], v[198:201], v[28:31]
	v_mfma_f32_16x16x32_bf16 v[24:27], v[182:185], v[198:201], v[24:27]
	v_mfma_f32_16x16x32_bf16 v[12:15], v[174:177], v[206:209], v[12:15]
	v_mfma_f32_16x16x32_bf16 v[8:11], v[182:185], v[206:209], v[8:11]
	v_mfma_f32_16x16x32_bf16 v[4:7], v[174:177], v[214:217], v[4:7]
	v_mfma_f32_16x16x32_bf16 v[0:3], v[182:185], v[214:217], v[0:3]
	v_mfma_f32_16x16x32_bf16 v[44:47], v[178:181], v[194:197], v[44:47]
	v_mfma_f32_16x16x32_bf16 v[40:43], v[186:189], v[194:197], v[40:43]
	v_mfma_f32_16x16x32_bf16 v[28:31], v[178:181], v[202:205], v[28:31]
	v_mfma_f32_16x16x32_bf16 v[24:27], v[186:189], v[202:205], v[24:27]
	v_mfma_f32_16x16x32_bf16 v[12:15], v[178:181], v[210:213], v[12:15]
	v_mfma_f32_16x16x32_bf16 v[8:11], v[186:189], v[210:213], v[8:11]
	v_mfma_f32_16x16x32_bf16 v[4:7], v[178:181], v[218:221], v[4:7]
	v_mfma_f32_16x16x32_bf16 v[0:3], v[186:189], v[218:221], v[0:3]
	s_barrier
	s_add_i32 s71, 0, 0x18000
	v_add_u32_e32 v151, s71, v146
	s_add_i32 s72, 0, 0x1c000
	ds_read_b128 v[152:155], v151
	ds_read_b128 v[156:159], v151 offset:1024
	ds_read_b128 v[164:167], v151 offset:2048
	ds_read_b128 v[170:173], v151 offset:3072
	v_add_u32_e32 v151, s72, v146
	ds_read_b128 v[174:177], v151
	ds_read_b128 v[178:181], v151 offset:1024
	ds_read_b128 v[182:185], v151 offset:2048
	ds_read_b128 v[186:189], v151 offset:3072
	s_add_u32 s24, s24, 0x80000
	s_addc_u32 s25, s25, 0
	s_mov_b32 m0, s40
	v_lshl_add_u64 v[230:231], s[24:25], 0, v[128:129]
	ds_read_b128 v[190:193], v150 offset:32768
	ds_read_b128 v[194:197], v150 offset:33792
	ds_read_b128 v[198:201], v150 offset:34816
	ds_read_b128 v[202:205], v150 offset:35840
	ds_read_b128 v[206:209], v150 offset:36864
	ds_read_b128 v[210:213], v150 offset:37888
	ds_read_b128 v[214:217], v150 offset:38912
	ds_read_b128 v[218:221], v150 offset:39936
	global_load_lds_dwordx4 v[230:231], off
	v_lshl_add_u64 v[230:231], s[24:25], 0, v[132:133]
	s_mov_b32 m0, s41
	s_nop 0
	global_load_lds_dwordx4 v[230:231], off
	s_waitcnt vmcnt(8)
	s_waitcnt lgkmcnt(0)
	s_barrier
	s_waitcnt lgkmcnt(0)
	v_mfma_f32_16x16x32_bf16 v[124:127], v[152:155], v[190:193], v[124:127]
	v_mfma_f32_16x16x32_bf16 v[120:123], v[164:167], v[190:193], v[120:123]
	v_mfma_f32_16x16x32_bf16 v[116:119], v[152:155], v[198:201], v[116:119]
	v_mfma_f32_16x16x32_bf16 v[112:115], v[164:167], v[198:201], v[112:115]
	v_mfma_f32_16x16x32_bf16 v[100:103], v[152:155], v[206:209], v[100:103]
	v_mfma_f32_16x16x32_bf16 v[96:99], v[164:167], v[206:209], v[96:99]
	v_mfma_f32_16x16x32_bf16 v[84:87], v[152:155], v[214:217], v[84:87]
	v_mfma_f32_16x16x32_bf16 v[80:83], v[164:167], v[214:217], v[80:83]
	v_mfma_f32_16x16x32_bf16 v[124:127], v[156:159], v[194:197], v[124:127]
	v_mfma_f32_16x16x32_bf16 v[120:123], v[170:173], v[194:197], v[120:123]
	v_mfma_f32_16x16x32_bf16 v[116:119], v[156:159], v[202:205], v[116:119]
	v_mfma_f32_16x16x32_bf16 v[112:115], v[170:173], v[202:205], v[112:115]
	v_mfma_f32_16x16x32_bf16 v[100:103], v[156:159], v[210:213], v[100:103]
	v_mfma_f32_16x16x32_bf16 v[96:99], v[170:173], v[210:213], v[96:99]
	v_mfma_f32_16x16x32_bf16 v[84:87], v[156:159], v[218:221], v[84:87]
	v_mfma_f32_16x16x32_bf16 v[80:83], v[170:173], v[218:221], v[80:83]
	v_mfma_f32_16x16x32_bf16 v[108:111], v[174:177], v[190:193], v[108:111]
	v_mfma_f32_16x16x32_bf16 v[104:107], v[182:185], v[190:193], v[104:107]
	v_mfma_f32_16x16x32_bf16 v[92:95], v[174:177], v[198:201], v[92:95]
	v_mfma_f32_16x16x32_bf16 v[88:91], v[182:185], v[198:201], v[88:91]
	v_mfma_f32_16x16x32_bf16 v[76:79], v[174:177], v[206:209], v[76:79]
	v_mfma_f32_16x16x32_bf16 v[72:75], v[182:185], v[206:209], v[72:75]
	v_mfma_f32_16x16x32_bf16 v[68:71], v[174:177], v[214:217], v[68:71]
	v_mfma_f32_16x16x32_bf16 v[64:67], v[182:185], v[214:217], v[64:67]
	v_mfma_f32_16x16x32_bf16 v[108:111], v[178:181], v[194:197], v[108:111]
	v_mfma_f32_16x16x32_bf16 v[104:107], v[186:189], v[194:197], v[104:107]
	v_mfma_f32_16x16x32_bf16 v[92:95], v[178:181], v[202:205], v[92:95]
	v_mfma_f32_16x16x32_bf16 v[88:91], v[186:189], v[202:205], v[88:91]
	v_mfma_f32_16x16x32_bf16 v[76:79], v[178:181], v[210:213], v[76:79]
	v_mfma_f32_16x16x32_bf16 v[72:75], v[186:189], v[210:213], v[72:75]
	v_mfma_f32_16x16x32_bf16 v[68:71], v[178:181], v[218:221], v[68:71]
	v_mfma_f32_16x16x32_bf16 v[64:67], v[186:189], v[218:221], v[64:67]
	s_barrier
; #define PG8_STAGE(bufoff, gbase, voff) do { _Pragma("unroll") for (int _i = 0; _i < 2; ++_i) \
;         __builtin_amdgcn_global_load_lds((const unsigned*)((const char*)(gbase) + (voff)[_i]), (LAS unsigned*)(lds + (bufoff) + ldsw + _i * 8192), 16, 0, 0); } while (0)
; #define PG8_LDA(dst, b, h) do { _Pragma("unroll") for (int m = 0; m < 4; ++m) _Pragma("unroll") for (int k = 0; k < 2; ++k) dst[m][k] = *(const LAS bf16x8*)(lds + PG8_SA(b, h) + aoff + m * 2048 + k * 1024); } while (0)
; #define PG8_WAIT_V(n) asm volatile("s_waitcnt vmcnt(" #n ")" ::: "memory")
; template <class Epi, class Sched, bool ALIGN_EPI = false, bool SP2 = false>
; __device__ __forceinline__ void gemm_phase(LAS unsigned char* lds, const Gemm g, const Sched& S, const Epi& E) {
;     ...
;             PG8_LDA(At, 1, 1); PG8_STAGE(PG8_SB(1, 0), b3, voffB); PG8_STAGE(PG8_SB(1, 1), b3 + hstep, voffB); PG8_STAGE(PG8_SA(1, 0), a3, voffA);
;             PG8_WAIT_V(8); PG8_WAIT_L(0); PG8_BAR; PG8_MMA(1, 0, At, B0); PG8_MMA(1, 1, At, B1); PG8_BAR; PG8_SCHED;
;             } else {
;             PG8_LDB(B0, 0, 0); PG8_SCHED; PG8_LDA(At, 0, 0); PG8_STAGE(PG8_SA(1, 1), a1 + hstep, voffA);
;             PG8_WAIT_L(8); PG8_BAR; PG8_WAIT_L(0); PG8_MMA(0, 0, At, B0); PG8_BAR; PG8_SCHED;
;             PG8_LDB(B1, 0, 1); PG8_STAGE(PG8_SB(0, 0), b2, voffB);
;             PG8_BAR; PG8_WAIT_L(0); PG8_MMA(0, 1, At, B1); PG8_BAR;
;             PG8_LDA(At, 0, 1); PG8_STAGE(PG8_SA(0, 0), a2, voffA);
;             PG8_BAR; PG8_WAIT_L(0); PG8_MMA(1, 0, At, B0); PG8_BAR; PG8_SCHED;
;             PG8_STAGE(PG8_SB(0, 1), b2 + hstep, voffB);
;             PG8_WAIT_V(6); PG8_BAR; PG8_MMA(1, 1, At, B1); PG8_BAR;
;             PG8_LDB(B0, 1, 0); PG8_SCHED; PG8_LDA(At, 1, 0); PG8_STAGE(PG8_SA(0, 1), a2 + hstep, voffA);
;             PG8_WAIT_L(8); PG8_BAR; PG8_WAIT_L(0); PG8_MMA(0, 0, At, B0); PG8_BAR; PG8_SCHED;
;             PG8_LDB(B1, 1, 1); PG8_STAGE(PG8_SB(1, 0), b3, voffB);
;             PG8_BAR; PG8_WAIT_L(0); PG8_MMA(0, 1, At, B1); PG8_BAR;
;             PG8_LDA(At, 1, 1); PG8_STAGE(PG8_SA(1, 0), a3, voffA);
;             PG8_BAR; PG8_WAIT_L(0); PG8_MMA(1, 0, At, B0); PG8_BAR; PG8_SCHED;
;             PG8_STAGE(PG8_SB(1, 1), b3 + hstep, voffB);
;             PG8_WAIT_V(6); PG8_BAR; PG8_MMA(1, 1, At, B1); PG8_BAR;
;             }
;         }
;         if constexpr (ALIGN_EPI) { if (wr == 0) PG8_BAR; }
	s_add_i32 s24, s71, s31
	v_lshl_add_u64 v[222:223], v[222:223], 0, s[4:5]
	s_mov_b32 m0, s24
	ds_read_b128 v[190:193], v150 offset:49152
	ds_read_b128 v[194:197], v150 offset:50176
	ds_read_b128 v[198:201], v150 offset:51200
	ds_read_b128 v[202:205], v150 offset:52224
	ds_read_b128 v[206:209], v150 offset:53248
	ds_read_b128 v[210:213], v150 offset:54272
	ds_read_b128 v[214:217], v150 offset:55296
	ds_read_b128 v[218:221], v150 offset:56320
	global_load_lds_dwordx4 v[222:223], off
	s_add_i32 m0, s24, 0x2000
	s_add_u32 s22, s22, 0x80080
	v_lshl_add_u64 v[222:223], v[224:225], 0, s[4:5]
	s_addc_u32 s23, s23, 0
	s_add_i32 s24, s72, s31
	global_load_lds_dwordx4 v[222:223], off
	v_lshl_add_u64 v[222:223], s[22:23], 0, v[130:131]
	s_mov_b32 m0, s24
	s_nop 0
	global_load_lds_dwordx4 v[222:223], off
	v_lshl_add_u64 v[222:223], s[22:23], 0, v[134:135]
	s_add_i32 m0, s24, 0x2000
	s_nop 0
	global_load_lds_dwordx4 v[222:223], off
	v_lshl_add_u64 v[222:223], v[226:227], 0, s[4:5]
	s_mov_b32 m0, s54
	s_nop 0
	global_load_lds_dwordx4 v[222:223], off
	v_lshl_add_u64 v[222:223], v[228:229], 0, s[4:5]
	s_mov_b32 m0, s55
	s_nop 0
	global_load_lds_dwordx4 v[222:223], off
	s_waitcnt vmcnt(8)
	s_waitcnt lgkmcnt(0)
	s_barrier
	s_waitcnt lgkmcnt(0)
	v_mfma_f32_16x16x32_bf16 v[60:63], v[152:155], v[190:193], v[60:63]
	v_mfma_f32_16x16x32_bf16 v[56:59], v[164:167], v[190:193], v[56:59]
	v_mfma_f32_16x16x32_bf16 v[52:55], v[152:155], v[198:201], v[52:55]
	v_mfma_f32_16x16x32_bf16 v[48:51], v[164:167], v[198:201], v[48:51]
	v_mfma_f32_16x16x32_bf16 v[36:39], v[152:155], v[206:209], v[36:39]
	v_mfma_f32_16x16x32_bf16 v[32:35], v[164:167], v[206:209], v[32:35]
	v_mfma_f32_16x16x32_bf16 v[20:23], v[152:155], v[214:217], v[20:23]
	v_mfma_f32_16x16x32_bf16 v[16:19], v[164:167], v[214:217], v[16:19]
	v_mfma_f32_16x16x32_bf16 v[60:63], v[156:159], v[194:197], v[60:63]
	v_mfma_f32_16x16x32_bf16 v[56:59], v[170:173], v[194:197], v[56:59]
	v_mfma_f32_16x16x32_bf16 v[52:55], v[156:159], v[202:205], v[52:55]
	v_mfma_f32_16x16x32_bf16 v[48:51], v[170:173], v[202:205], v[48:51]
	v_mfma_f32_16x16x32_bf16 v[36:39], v[156:159], v[210:213], v[36:39]
	v_mfma_f32_16x16x32_bf16 v[32:35], v[170:173], v[210:213], v[32:35]
	v_mfma_f32_16x16x32_bf16 v[20:23], v[156:159], v[218:221], v[20:23]
	v_mfma_f32_16x16x32_bf16 v[16:19], v[170:173], v[218:221], v[16:19]
	v_mfma_f32_16x16x32_bf16 v[44:47], v[174:177], v[190:193], v[44:47]
	v_mfma_f32_16x16x32_bf16 v[40:43], v[182:185], v[190:193], v[40:43]
	v_mfma_f32_16x16x32_bf16 v[28:31], v[174:177], v[198:201], v[28:31]
	v_mfma_f32_16x16x32_bf16 v[24:27], v[182:185], v[198:201], v[24:27]
	v_mfma_f32_16x16x32_bf16 v[12:15], v[174:177], v[206:209], v[12:15]
	v_mfma_f32_16x16x32_bf16 v[8:11], v[182:185], v[206:209], v[8:11]
	v_mfma_f32_16x16x32_bf16 v[4:7], v[174:177], v[214:217], v[4:7]
	v_mfma_f32_16x16x32_bf16 v[0:3], v[182:185], v[214:217], v[0:3]
	v_mfma_f32_16x16x32_bf16 v[44:47], v[178:181], v[194:197], v[44:47]
	v_mfma_f32_16x16x32_bf16 v[40:43], v[186:189], v[194:197], v[40:43]
	v_mfma_f32_16x16x32_bf16 v[28:31], v[178:181], v[202:205], v[28:31]
	v_mfma_f32_16x16x32_bf16 v[24:27], v[186:189], v[202:205], v[24:27]
	v_mfma_f32_16x16x32_bf16 v[12:15], v[178:181], v[210:213], v[12:15]
	v_mfma_f32_16x16x32_bf16 v[8:11], v[186:189], v[210:213], v[8:11]
	v_mfma_f32_16x16x32_bf16 v[4:7], v[178:181], v[218:221], v[4:7]
	v_mfma_f32_16x16x32_bf16 v[0:3], v[186:189], v[218:221], v[0:3]
	s_barrier
	s_add_i32 s70, s70, 2
	s_add_u32 s20, s20, 0x100
	s_addc_u32 s21, s21, 0
	s_add_u32 s29, s29, 0x100
	s_addc_u32 s69, s69, 0
	s_cmp_gt_u32 s70, 29
	s_cbranch_scc0 .LBB0_220
	s_and_b64 vcc, exec, s[6:7]
	s_cbranch_vccz .LBB0_223
	s_barrier

; __device__ __forceinline__ unsigned xb_add(unsigned* p, unsigned v) { return __hip_atomic_fetch_add(p, v, __ATOMIC_RELAXED, __HIP_MEMORY_SCOPE_AGENT); }
; #define GSYNC() xcd_barrier(xb)
; #define SEAM(k) do { if (IN(k) && IN((k) + 1)) GSYNC(); } while (0)
; __device__ __forceinline__ void xcd_barrier(const XcdBarrier& b) {
;     asm volatile("s_waitcnt vmcnt(0)" ::: "memory");
;     __syncthreads();
;     if (threadIdx.x == 0) {
;         unsigned* bar = b.bar;
;         __builtin_amdgcn_s_waitcnt(0);
;         unsigned nloc = b.st[0], nx = b.st[1];
;         if (nloc == 0u) { xcd_barrier_complete(bar, b.x, nloc, nx); b.st[0] = nloc; b.st[1] = nx; }
;         const unsigned old = xb_add(&bar[XB_XSUB(b.x)], 1u);
;         const unsigned gen = old / nloc;
;         if (old + 1u == (gen + 1u) * nloc) {
;             __builtin_amdgcn_fence(__ATOMIC_RELEASE, "agent");
; __global__ void __launch_bounds__(512, 2) fwd_megakernel(Params p) {
;     ...
;     if (IN(0)) { for (int rep_ = 0; rep_ < NREP(0); ++rep_) { if (rep_) GSYNC(); if (PH(0)) phase_mod(p, lds, 0, 0, gridDim.x); } } SEAM(0);
;     if (IN(1)) { for (int rep_ = 0; rep_ < NREP(1); ++rep_) { if (rep_) GSYNC(); if (PH(1)) { phase_convert(p, lds, 0, 0, gridDim.x); phase_modulate(p, p.x, p.ctx, p.norm1_g, 0, 0, MALL, -1, 0); } } } SEAM(1);
;     if (IN(2)) { for (int rep_ = 0; rep_ < NREP(2); ++rep_) { if (rep_) GSYNC(); if (PH(2)) run_gemm_store(p, ldsl, 2); } } SEAM(2);
.LBB0_227:
	s_setprio 0
	s_cmp_gt_i32 s81, 3
	s_cselect_b64 s[2:3], -1, 0
	s_and_b64 s[0:1], s[0:1], s[2:3]
	s_andn2_b64 vcc, exec, s[0:1]
	s_cbranch_vccnz .LBB0_281
	s_waitcnt vmcnt(0)
	s_waitcnt vmcnt(0)
	s_barrier
	s_and_saveexec_b64 s[0:1], s[94:95]
	s_cbranch_execz .LBB0_280
	s_add_i32 s4, 0, 0x23fc0
	v_mov_b32_e32 v0, s4
	s_waitcnt vmcnt(0) expcnt(0) lgkmcnt(0)
	ds_read_b32 v2, v0
	s_add_i32 s4, 0, 0x23fc4
	v_mov_b32_e32 v0, s4
	ds_read_b32 v0, v0
	s_waitcnt lgkmcnt(1)
	v_cmp_ne_u32_e32 vcc, 0, v2
	s_cbranch_vccnz .LBB0_244
	v_readlane_b32 s4, v241, 0
	s_mul_i32 s33, s83, s4
	s_add_u32 s4, s90, 0x88200
	s_addc_u32 s5, s91, 0
	s_add_u32 s6, s90, 0x88400
	s_addc_u32 s7, s91, 0
	s_add_u32 s8, s90, 0x88500
	s_addc_u32 s9, s91, 0
	s_add_u32 s10, s90, 0x88600
	s_addc_u32 s11, s91, 0
	s_add_u32 s12, s90, 0x88700
	s_addc_u32 s13, s91, 0
	s_add_u32 s14, s90, 0x88800
	s_addc_u32 s15, s91, 0
	s_add_u32 s16, s90, 0x88900
	s_addc_u32 s17, s91, 0
	s_add_u32 s18, s90, 0x88a00
	s_addc_u32 s19, s91, 0
	s_add_u32 s20, s90, 0x88b00
	s_addc_u32 s21, s91, 0
	s_add_u32 s22, s90, 0x88c00
	s_addc_u32 s23, s91, 0
	s_add_u32 s24, s90, 0x88d00
	s_addc_u32 s25, s91, 0
	s_add_u32 s26, s90, 0x88e00
	s_addc_u32 s27, s91, 0
	s_add_u32 s28, s90, 0x88f00
	s_addc_u32 s29, s91, 0
	s_add_u32 s30, s90, 0x89000
	s_addc_u32 s31, s91, 0
	s_add_u32 s34, s90, 0x89100
	s_addc_u32 s35, s91, 0
	s_add_u32 s40, s90, 0x89200
	s_addc_u32 s41, s91, 0
	s_add_u32 s42, s90, 0x89300
	s_mul_i32 s33, s33, s82
	s_addc_u32 s43, s91, 0
	s_mov_b32 s70, 1
	v_mov_b32_e32 v16, 0
	s_branch .LBB0_232

; #define LAS __attribute__((address_space(3)))
; #define GSYNC() xcd_barrier(xb)
; #define SEAM(k) do { if (IN(k) && IN((k) + 1)) GSYNC(); } while (0)
; __device__ __forceinline__ void run_gemm_resid(const Params& p, LAS unsigned char* ldsl, const int ph) {
;     unsigned char* ws = p.ws; const int l1 = ph >= 9;
;     const float* modl = (const float*)(ws + WS_MODV) + (size_t)l1 * 5 * (6 * D);
;     float* xcb = (float*)(ws + WS_XC);
;     const bool dn = (ph == 8 || ph == 15);
;     const int K = dn ? DFF : D;
;     const bf16_t* A = dn ? (const bf16_t*)(ws + WS_H) : (const bf16_t*)(ws + WS_A);
;     const bf16_t* Bt = dn ? (const bf16_t*)(ws + WS_WDN) + (size_t)l1 * D * DFF : (ph == 5 ? (const bf16_t*)(ws + WS_WOUT) : (const bf16_t*)(ws + WS_WNO));
;     pg8::Gemm g{K}; pg8::SegOrder S; S.init(K, gridDim.x, blockIdx.x);
;     S.add(A, Bt, MLAT / 256, D / 256, 1, K / 64, 0);
;     if (!l1) S.add(A + (size_t)MLAT * K, Bt, MCTX / 256, D / 256, 8, K / 64 / 8, 1);
;     pg8::EpiResid E{ph == 5 ? p.x : p.out, p.out, (float*)(ws + WS_PART), modl + (dn ? 5 : 2) * D};
;     pg8::gemm_phase<pg8::EpiResid, pg8::SegOrder, true, true>(ldsl, g, S, E);
; __global__ void __launch_bounds__(512, 2) fwd_megakernel(Params p) {
;     ...
;     if (IN(5)) { for (int rep_ = 0; rep_ < NREP(5); ++rep_) { if (rep_) GSYNC(); if (PH(5)) run_gemm_resid(p, ldsl, 5); } } SEAM(5);
.LBB0_714:
	s_cmp_lt_i32 s80, 6
	s_cselect_b64 s[2:3], -1, 0
	s_and_b64 s[0:1], s[2:3], s[0:1]
	s_andn2_b64 vcc, exec, s[0:1]
	s_mov_b32 s10, 1
	s_cbranch_vccnz .LBB0_745
	v_readfirstlane_b32 s101, v162
	s_nop 3
	s_lshr_b32 s101, s101, 6
	s_cmp_ge_u32 s101, 4
	s_cbranch_scc0 .Lsp_16257
	s_setprio 1
.Lsp_16257:
	s_ashr_i32 s33, s92, 31
	s_cmpk_lt_i32 s92, 0x200
	s_cselect_b64 s[6:7], -1, 0
	v_readfirstlane_b32 s9, v162
	s_and_b64 vcc, exec, s[6:7]
	s_cbranch_vccnz .LBB0_717
	s_add_u32 s2, s92, 0xfffffe00
	s_addc_u32 s3, s33, -1
	v_mov_b64_e32 v[0:1], 0x100
	v_cmp_lt_u64_e64 s[6:7], s[2:3], v[0:1]
	s_mov_b32 s19, 1
	s_mov_b32 s10, 8
	s_mov_b32 s8, 4
	s_mov_b64 s[4:5], 0x10600000
	s_mov_b32 s62, 4
	s_andn2_b64 vcc, exec, s[6:7]
	s_cbranch_vccz .LBB0_718
	s_branch .LBB0_745

; #define PG8_STAGE(bufoff, gbase, voff) do { _Pragma("unroll") for (int _i = 0; _i < 2; ++_i) \
;         __builtin_amdgcn_global_load_lds((const unsigned*)((const char*)(gbase) + (voff)[_i]), (LAS unsigned*)(lds + (bufoff) + ldsw + _i * 8192), 16, 0, 0); } while (0)
; #define PG8_LDA(dst, b, h) do { _Pragma("unroll") for (int m = 0; m < 4; ++m) _Pragma("unroll") for (int k = 0; k < 2; ++k) dst[m][k] = *(const LAS bf16x8*)(lds + PG8_SA(b, h) + aoff + m * 2048 + k * 1024); } while (0)
; #define PG8_LDB(dst, b, h) do { _Pragma("unroll") for (int n = 0; n < 2; ++n) _Pragma("unroll") for (int k = 0; k < 2; ++k) dst[n][k] = *(const LAS bf16x8*)(lds + PG8_SB(b, h) + boff + n * 2048 + k * 1024); } while (0)
; #define PG8_MMA(ai, bj, At, Bt) do { __builtin_amdgcn_s_setprio(1); _Pragma("unroll") for (int m = 0; m < 4; ++m) _Pragma("unroll") for (int n = 0; n < 2; ++n) _Pragma("unroll") for (int k = 0; k < 2; ++k) \
;         acc[ai][bj][m][n] = __builtin_amdgcn_mfma_f32_16x16x32_bf16(Bt[n][k], At[m][k], acc[ai][bj][m][n], 0, 0, 0); __builtin_amdgcn_s_setprio(0); } while (0)
; #define PG8_WAIT_V(n) asm volatile("s_waitcnt vmcnt(" #n ")" ::: "memory")
; #define PG8_WAIT_L(n) asm volatile("s_waitcnt lgkmcnt(" #n ")" ::: "memory")
; #define PG8_BAR __builtin_amdgcn_s_barrier()
; #define PG8_SCHED __builtin_amdgcn_sched_barrier(0)
; template <class Epi, class Sched, bool ALIGN_EPI = false, bool SP2 = false>
; __device__ __forceinline__ void gemm_phase(LAS unsigned char* lds, const Gemm g, const Sched& S, const Epi& E) {
;     ...
;             PG8_LDB(B0, 0, 0); PG8_LDB(B1, 0, 1); PG8_SCHED; PG8_LDA(At, 0, 0); PG8_STAGE(PG8_SA(1, 1), a1 + hstep, voffA);
;             PG8_WAIT_V(8); PG8_WAIT_L(0); PG8_BAR; PG8_MMA(0, 0, At, B0); PG8_MMA(0, 1, At, B1); PG8_BAR; PG8_SCHED;
;             PG8_LDA(At, 0, 1); PG8_STAGE(PG8_SB(0, 0), b2, voffB); PG8_STAGE(PG8_SB(0, 1), b2 + hstep, voffB); PG8_STAGE(PG8_SA(0, 0), a2, voffA);
.LBB0_731:
	ds_read_b128 v[128:131], v166
	ds_read_b128 v[132:135], v166 offset:1024
	ds_read_b128 v[136:139], v166 offset:2048
	ds_read_b128 v[140:143], v166 offset:3072
	ds_read_b128 v[172:175], v167
	ds_read_b128 v[176:179], v167 offset:1024
	ds_read_b128 v[180:183], v167 offset:2048
	ds_read_b128 v[184:187], v167 offset:3072
	s_add_i32 s66, s26, 2
	s_add_u32 s27, s24, 0xfff80080
	s_addc_u32 s28, s25, -1
	s_cmp_eq_u32 s63, s26
	s_cselect_b32 s26, s35, s64
	s_cselect_b32 s29, s30, s28
	s_cselect_b32 s28, s31, s27
	s_cselect_b32 s27, s34, s65
	v_lshl_add_u64 v[158:159], s[24:25], 0, v[150:151]
	s_add_i32 m0, s39, 0xc000
	ds_read_b128 v[188:191], v168
	ds_read_b128 v[192:195], v168 offset:1024
	ds_read_b128 v[196:199], v168 offset:2048
	ds_read_b128 v[200:203], v168 offset:3072
	ds_read_b128 v[204:207], v168 offset:4096
	ds_read_b128 v[208:211], v168 offset:5120
	ds_read_b128 v[212:215], v168 offset:6144
	ds_read_b128 v[216:219], v168 offset:7168
	global_load_lds_dwordx4 v[158:159], off
	v_lshl_add_u64 v[158:159], s[24:25], 0, v[152:153]
	s_add_i32 m0, s39, 0xe000
	s_nop 0
	global_load_lds_dwordx4 v[158:159], off
	s_waitcnt vmcnt(8)
	s_waitcnt lgkmcnt(0)
	s_barrier
	s_waitcnt lgkmcnt(0)
	v_mfma_f32_16x16x32_bf16 v[124:127], v[128:131], v[188:191], v[124:127]
	v_mfma_f32_16x16x32_bf16 v[120:123], v[136:139], v[188:191], v[120:123]
	v_mfma_f32_16x16x32_bf16 v[116:119], v[128:131], v[196:199], v[116:119]
	v_mfma_f32_16x16x32_bf16 v[112:115], v[136:139], v[196:199], v[112:115]
	v_mfma_f32_16x16x32_bf16 v[108:111], v[128:131], v[204:207], v[108:111]
	v_mfma_f32_16x16x32_bf16 v[96:99], v[136:139], v[204:207], v[96:99]
	v_mfma_f32_16x16x32_bf16 v[80:83], v[128:131], v[212:215], v[80:83]
	v_mfma_f32_16x16x32_bf16 v[72:75], v[136:139], v[212:215], v[72:75]
	v_mfma_f32_16x16x32_bf16 v[124:127], v[132:135], v[192:195], v[124:127]
	v_mfma_f32_16x16x32_bf16 v[120:123], v[140:143], v[192:195], v[120:123]
	v_mfma_f32_16x16x32_bf16 v[116:119], v[132:135], v[200:203], v[116:119]
	v_mfma_f32_16x16x32_bf16 v[112:115], v[140:143], v[200:203], v[112:115]
	v_mfma_f32_16x16x32_bf16 v[108:111], v[132:135], v[208:211], v[108:111]
	v_mfma_f32_16x16x32_bf16 v[96:99], v[140:143], v[208:211], v[96:99]
	v_mfma_f32_16x16x32_bf16 v[80:83], v[132:135], v[216:219], v[80:83]
	v_mfma_f32_16x16x32_bf16 v[72:75], v[140:143], v[216:219], v[72:75]
	v_mfma_f32_16x16x32_bf16 v[104:107], v[172:175], v[188:191], v[104:107]
	v_mfma_f32_16x16x32_bf16 v[100:103], v[180:183], v[188:191], v[100:103]
	v_mfma_f32_16x16x32_bf16 v[92:95], v[172:175], v[196:199], v[92:95]
	v_mfma_f32_16x16x32_bf16 v[88:91], v[180:183], v[196:199], v[88:91]
	v_mfma_f32_16x16x32_bf16 v[84:87], v[172:175], v[204:207], v[84:87]
	v_mfma_f32_16x16x32_bf16 v[76:79], v[180:183], v[204:207], v[76:79]
	v_mfma_f32_16x16x32_bf16 v[68:71], v[172:175], v[212:215], v[68:71]
	v_mfma_f32_16x16x32_bf16 v[64:67], v[180:183], v[212:215], v[64:67]
	v_mfma_f32_16x16x32_bf16 v[104:107], v[176:179], v[192:195], v[104:107]
	v_mfma_f32_16x16x32_bf16 v[100:103], v[184:187], v[192:195], v[100:103]
	v_mfma_f32_16x16x32_bf16 v[92:95], v[176:179], v[200:203], v[92:95]
	v_mfma_f32_16x16x32_bf16 v[88:91], v[184:187], v[200:203], v[88:91]
	v_mfma_f32_16x16x32_bf16 v[84:87], v[176:179], v[208:211], v[84:87]
	v_mfma_f32_16x16x32_bf16 v[76:79], v[184:187], v[208:211], v[76:79]
	v_mfma_f32_16x16x32_bf16 v[68:71], v[176:179], v[216:219], v[68:71]
	v_mfma_f32_16x16x32_bf16 v[64:67], v[184:187], v[216:219], v[64:67]
	s_barrier
	s_add_i32 s67, s51, s38
	v_lshl_add_u64 v[158:159], s[26:27], 0, v[144:145]
	s_mov_b32 m0, s67
	ds_read_b128 v[188:191], v168 offset:16384
	ds_read_b128 v[192:195], v168 offset:17408
	ds_read_b128 v[196:199], v168 offset:18432
	ds_read_b128 v[200:203], v168 offset:19456
	ds_read_b128 v[204:207], v168 offset:20480
	ds_read_b128 v[208:211], v168 offset:21504
	ds_read_b128 v[212:215], v168 offset:22528
	ds_read_b128 v[216:219], v168 offset:23552
	global_load_lds_dwordx4 v[158:159], off
	s_add_i32 m0, s67, 0x2000
	s_add_u32 s68, s26, 0x80000
	v_lshl_add_u64 v[164:165], s[26:27], 0, v[146:147]
	s_addc_u32 s69, s27, 0
	s_add_i32 s67, s52, s38
	global_load_lds_dwordx4 v[164:165], off
	v_lshl_add_u64 v[220:221], s[68:69], 0, v[144:145]
	s_mov_b32 m0, s67
	v_lshl_add_u64 v[222:223], s[28:29], 0, v[146:147]
	global_load_lds_dwordx4 v[220:221], off
	v_lshl_add_u64 v[220:221], s[68:69], 0, v[146:147]
	s_add_i32 m0, s67, 0x2000
	s_nop 0
	global_load_lds_dwordx4 v[220:221], off
	v_lshl_add_u64 v[220:221], s[28:29], 0, v[144:145]
	s_mov_b32 m0, s39
	s_nop 0
	global_load_lds_dwordx4 v[220:221], off
	s_mov_b32 m0, s40
	s_nop 0
	global_load_lds_dwordx4 v[222:223], off
	s_waitcnt vmcnt(8)
	s_waitcnt lgkmcnt(0)
	s_barrier
; #define PG8_STAGE(bufoff, gbase, voff) do { _Pragma("unroll") for (int _i = 0; _i < 2; ++_i) \
;         __builtin_amdgcn_global_load_lds((const unsigned*)((const char*)(gbase) + (voff)[_i]), (LAS unsigned*)(lds + (bufoff) + ldsw + _i * 8192), 16, 0, 0); } while (0)
; #define PG8_LDA(dst, b, h) do { _Pragma("unroll") for (int m = 0; m < 4; ++m) _Pragma("unroll") for (int k = 0; k < 2; ++k) dst[m][k] = *(const LAS bf16x8*)(lds + PG8_SA(b, h) + aoff + m * 2048 + k * 1024); } while (0)
; #define PG8_LDB(dst, b, h) do { _Pragma("unroll") for (int n = 0; n < 2; ++n) _Pragma("unroll") for (int k = 0; k < 2; ++k) dst[n][k] = *(const LAS bf16x8*)(lds + PG8_SB(b, h) + boff + n * 2048 + k * 1024); } while (0)
; #define PG8_MMA(ai, bj, At, Bt) do { __builtin_amdgcn_s_setprio(1); _Pragma("unroll") for (int m = 0; m < 4; ++m) _Pragma("unroll") for (int n = 0; n < 2; ++n) _Pragma("unroll") for (int k = 0; k < 2; ++k) \
;         acc[ai][bj][m][n] = __builtin_amdgcn_mfma_f32_16x16x32_bf16(Bt[n][k], At[m][k], acc[ai][bj][m][n], 0, 0, 0); __builtin_amdgcn_s_setprio(0); } while (0)
; #define PG8_WAIT_V(n) asm volatile("s_waitcnt vmcnt(" #n ")" ::: "memory")
; #define PG8_WAIT_L(n) asm volatile("s_waitcnt lgkmcnt(" #n ")" ::: "memory")
; #define PG8_BAR __builtin_amdgcn_s_barrier()
; #define PG8_SCHED __builtin_amdgcn_sched_barrier(0)
; template <class Epi, class Sched, bool ALIGN_EPI = false, bool SP2 = false>
; __device__ __forceinline__ void gemm_phase(LAS unsigned char* lds, const Gemm g, const Sched& S, const Epi& E) {
;     ...
;             PG8_WAIT_V(8); PG8_WAIT_L(0); PG8_BAR; PG8_MMA(1, 0, At, B0); PG8_MMA(1, 1, At, B1); PG8_BAR; PG8_SCHED;
;             PG8_LDB(B0, 1, 0); PG8_LDB(B1, 1, 1); PG8_SCHED; PG8_LDA(At, 1, 0); PG8_STAGE(PG8_SA(0, 1), a2 + hstep, voffA);
;             PG8_WAIT_V(8); PG8_WAIT_L(0); PG8_BAR; PG8_MMA(0, 0, At, B0); PG8_MMA(0, 1, At, B1); PG8_BAR; PG8_SCHED;
	s_waitcnt lgkmcnt(0)
	v_mfma_f32_16x16x32_bf16 v[60:63], v[128:131], v[188:191], v[60:63]
	v_mfma_f32_16x16x32_bf16 v[56:59], v[136:139], v[188:191], v[56:59]
	v_mfma_f32_16x16x32_bf16 v[52:55], v[128:131], v[196:199], v[52:55]
	v_mfma_f32_16x16x32_bf16 v[48:51], v[136:139], v[196:199], v[48:51]
	v_mfma_f32_16x16x32_bf16 v[36:39], v[128:131], v[204:207], v[36:39]
	v_mfma_f32_16x16x32_bf16 v[24:27], v[136:139], v[204:207], v[24:27]
	v_mfma_f32_16x16x32_bf16 v[20:23], v[128:131], v[212:215], v[20:23]
	v_mfma_f32_16x16x32_bf16 v[8:11], v[136:139], v[212:215], v[8:11]
	v_mfma_f32_16x16x32_bf16 v[60:63], v[132:135], v[192:195], v[60:63]
	v_mfma_f32_16x16x32_bf16 v[56:59], v[140:143], v[192:195], v[56:59]
	v_mfma_f32_16x16x32_bf16 v[52:55], v[132:135], v[200:203], v[52:55]
	v_mfma_f32_16x16x32_bf16 v[48:51], v[140:143], v[200:203], v[48:51]
	v_mfma_f32_16x16x32_bf16 v[36:39], v[132:135], v[208:211], v[36:39]
	v_mfma_f32_16x16x32_bf16 v[24:27], v[140:143], v[208:211], v[24:27]
	v_mfma_f32_16x16x32_bf16 v[20:23], v[132:135], v[216:219], v[20:23]
	v_mfma_f32_16x16x32_bf16 v[8:11], v[140:143], v[216:219], v[8:11]
	v_mfma_f32_16x16x32_bf16 v[44:47], v[172:175], v[188:191], v[44:47]
	v_mfma_f32_16x16x32_bf16 v[40:43], v[180:183], v[188:191], v[40:43]
	v_mfma_f32_16x16x32_bf16 v[32:35], v[172:175], v[196:199], v[32:35]
	v_mfma_f32_16x16x32_bf16 v[28:31], v[180:183], v[196:199], v[28:31]
	v_mfma_f32_16x16x32_bf16 v[16:19], v[172:175], v[204:207], v[16:19]
	v_mfma_f32_16x16x32_bf16 v[12:15], v[180:183], v[204:207], v[12:15]
	v_mfma_f32_16x16x32_bf16 v[4:7], v[172:175], v[212:215], v[4:7]
	v_mfma_f32_16x16x32_bf16 v[0:3], v[180:183], v[212:215], v[0:3]
	v_mfma_f32_16x16x32_bf16 v[44:47], v[176:179], v[192:195], v[44:47]
	v_mfma_f32_16x16x32_bf16 v[40:43], v[184:187], v[192:195], v[40:43]
	v_mfma_f32_16x16x32_bf16 v[32:35], v[176:179], v[200:203], v[32:35]
	v_mfma_f32_16x16x32_bf16 v[28:31], v[184:187], v[200:203], v[28:31]
	v_mfma_f32_16x16x32_bf16 v[16:19], v[176:179], v[208:211], v[16:19]
	v_mfma_f32_16x16x32_bf16 v[12:15], v[184:187], v[208:211], v[12:15]
	v_mfma_f32_16x16x32_bf16 v[4:7], v[176:179], v[216:219], v[4:7]
	v_mfma_f32_16x16x32_bf16 v[0:3], v[184:187], v[216:219], v[0:3]
	s_barrier
	s_add_i32 s67, 0, 0x18000
	s_add_i32 s68, 0, 0x1c000
	v_add_u32_e32 v140, s67, v163
	v_add_u32_e32 v171, s68, v163
	ds_read_b128 v[128:131], v140
	ds_read_b128 v[132:135], v140 offset:1024
	ds_read_b128 v[136:139], v140 offset:2048
	ds_read_b128 v[140:143], v140 offset:3072
	ds_read_b128 v[172:175], v171
	ds_read_b128 v[176:179], v171 offset:1024
	ds_read_b128 v[180:183], v171 offset:2048
	ds_read_b128 v[184:187], v171 offset:3072
	s_add_u32 s28, s28, 0x80000
	s_addc_u32 s29, s29, 0
	s_mov_b32 m0, s41
	v_lshl_add_u64 v[224:225], s[28:29], 0, v[144:145]
	ds_read_b128 v[188:191], v168 offset:32768
	ds_read_b128 v[192:195], v168 offset:33792
	ds_read_b128 v[196:199], v168 offset:34816
	ds_read_b128 v[200:203], v168 offset:35840
	ds_read_b128 v[204:207], v168 offset:36864
	ds_read_b128 v[208:211], v168 offset:37888
	ds_read_b128 v[212:215], v168 offset:38912
	ds_read_b128 v[216:219], v168 offset:39936
	global_load_lds_dwordx4 v[224:225], off
	v_lshl_add_u64 v[224:225], s[28:29], 0, v[146:147]
	s_mov_b32 m0, s42
	s_nop 0
	global_load_lds_dwordx4 v[224:225], off
	s_waitcnt vmcnt(8)
	s_waitcnt lgkmcnt(0)
	s_barrier
	s_waitcnt lgkmcnt(0)
	v_mfma_f32_16x16x32_bf16 v[124:127], v[128:131], v[188:191], v[124:127]
	v_mfma_f32_16x16x32_bf16 v[120:123], v[136:139], v[188:191], v[120:123]
	v_mfma_f32_16x16x32_bf16 v[116:119], v[128:131], v[196:199], v[116:119]
	v_mfma_f32_16x16x32_bf16 v[112:115], v[136:139], v[196:199], v[112:115]
	v_mfma_f32_16x16x32_bf16 v[108:111], v[128:131], v[204:207], v[108:111]
	v_mfma_f32_16x16x32_bf16 v[96:99], v[136:139], v[204:207], v[96:99]
	v_mfma_f32_16x16x32_bf16 v[80:83], v[128:131], v[212:215], v[80:83]
	v_mfma_f32_16x16x32_bf16 v[72:75], v[136:139], v[212:215], v[72:75]
	v_mfma_f32_16x16x32_bf16 v[124:127], v[132:135], v[192:195], v[124:127]
	v_mfma_f32_16x16x32_bf16 v[120:123], v[140:143], v[192:195], v[120:123]
	v_mfma_f32_16x16x32_bf16 v[116:119], v[132:135], v[200:203], v[116:119]
	v_mfma_f32_16x16x32_bf16 v[112:115], v[140:143], v[200:203], v[112:115]
	v_mfma_f32_16x16x32_bf16 v[108:111], v[132:135], v[208:211], v[108:111]
	v_mfma_f32_16x16x32_bf16 v[96:99], v[140:143], v[208:211], v[96:99]
	v_mfma_f32_16x16x32_bf16 v[80:83], v[132:135], v[216:219], v[80:83]
	v_mfma_f32_16x16x32_bf16 v[72:75], v[140:143], v[216:219], v[72:75]
	v_mfma_f32_16x16x32_bf16 v[104:107], v[172:175], v[188:191], v[104:107]
	v_mfma_f32_16x16x32_bf16 v[100:103], v[180:183], v[188:191], v[100:103]
	v_mfma_f32_16x16x32_bf16 v[92:95], v[172:175], v[196:199], v[92:95]
	v_mfma_f32_16x16x32_bf16 v[88:91], v[180:183], v[196:199], v[88:91]
	v_mfma_f32_16x16x32_bf16 v[84:87], v[172:175], v[204:207], v[84:87]
	v_mfma_f32_16x16x32_bf16 v[76:79], v[180:183], v[204:207], v[76:79]
	v_mfma_f32_16x16x32_bf16 v[68:71], v[172:175], v[212:215], v[68:71]
	v_mfma_f32_16x16x32_bf16 v[64:67], v[180:183], v[212:215], v[64:67]
	v_mfma_f32_16x16x32_bf16 v[104:107], v[176:179], v[192:195], v[104:107]
	v_mfma_f32_16x16x32_bf16 v[100:103], v[184:187], v[192:195], v[100:103]
	v_mfma_f32_16x16x32_bf16 v[92:95], v[176:179], v[200:203], v[92:95]
	v_mfma_f32_16x16x32_bf16 v[88:91], v[184:187], v[200:203], v[88:91]
	v_mfma_f32_16x16x32_bf16 v[84:87], v[176:179], v[208:211], v[84:87]
	v_mfma_f32_16x16x32_bf16 v[76:79], v[184:187], v[208:211], v[76:79]
	v_mfma_f32_16x16x32_bf16 v[68:71], v[176:179], v[216:219], v[68:71]
	v_mfma_f32_16x16x32_bf16 v[64:67], v[184:187], v[216:219], v[64:67]
	s_barrier
; #define PG8_STAGE(bufoff, gbase, voff) do { _Pragma("unroll") for (int _i = 0; _i < 2; ++_i) \
;         __builtin_amdgcn_global_load_lds((const unsigned*)((const char*)(gbase) + (voff)[_i]), (LAS unsigned*)(lds + (bufoff) + ldsw + _i * 8192), 16, 0, 0); } while (0)
; #define PG8_LDA(dst, b, h) do { _Pragma("unroll") for (int m = 0; m < 4; ++m) _Pragma("unroll") for (int k = 0; k < 2; ++k) dst[m][k] = *(const LAS bf16x8*)(lds + PG8_SA(b, h) + aoff + m * 2048 + k * 1024); } while (0)
; #define PG8_MMA(ai, bj, At, Bt) do { __builtin_amdgcn_s_setprio(1); _Pragma("unroll") for (int m = 0; m < 4; ++m) _Pragma("unroll") for (int n = 0; n < 2; ++n) _Pragma("unroll") for (int k = 0; k < 2; ++k) \
;         acc[ai][bj][m][n] = __builtin_amdgcn_mfma_f32_16x16x32_bf16(Bt[n][k], At[m][k], acc[ai][bj][m][n], 0, 0, 0); __builtin_amdgcn_s_setprio(0); } while (0)
; #define PG8_WAIT_V(n) asm volatile("s_waitcnt vmcnt(" #n ")" ::: "memory")
; #define PG8_WAIT_L(n) asm volatile("s_waitcnt lgkmcnt(" #n ")" ::: "memory")
; #define PG8_BAR __builtin_amdgcn_s_barrier()
; #define PG8_SCHED __builtin_amdgcn_sched_barrier(0)
; template <class Epi, class Sched, bool ALIGN_EPI = false, bool SP2 = false>
; __device__ __forceinline__ void gemm_phase(LAS unsigned char* lds, const Gemm g, const Sched& S, const Epi& E) {
;     ...
;         for (int t = 0; t < nt; t += 2) {
;             const bool last = (t == nt - 2);
;             const char* a1 = cA + (size_t)(t + 1) * kstep;
;             const char* a2 = last ? nA : cA + (size_t)(t + 2) * kstep; const char* b2 = last ? nB : cB + (size_t)(t + 2) * kstep;
;             const char* a3 = a2 + kstep; const char* b3 = b2 + kstep;
;     ...
;             PG8_LDA(At, 1, 1); PG8_STAGE(PG8_SB(1, 0), b3, voffB); PG8_STAGE(PG8_SB(1, 1), b3 + hstep, voffB); PG8_STAGE(PG8_SA(1, 0), a3, voffA);
;             PG8_WAIT_V(8); PG8_WAIT_L(0); PG8_BAR; PG8_MMA(1, 0, At, B0); PG8_MMA(1, 1, At, B1); PG8_BAR; PG8_SCHED;
	s_add_i32 s28, s67, s38
	v_lshl_add_u64 v[158:159], v[158:159], 0, s[6:7]
	s_mov_b32 m0, s28
	ds_read_b128 v[188:191], v168 offset:49152
	ds_read_b128 v[192:195], v168 offset:50176
	ds_read_b128 v[196:199], v168 offset:51200
	ds_read_b128 v[200:203], v168 offset:52224
	ds_read_b128 v[204:207], v168 offset:53248
	ds_read_b128 v[208:211], v168 offset:54272
	ds_read_b128 v[212:215], v168 offset:55296
	ds_read_b128 v[216:219], v168 offset:56320
	global_load_lds_dwordx4 v[158:159], off
	s_add_i32 m0, s28, 0x2000
	s_add_u32 s26, s26, 0x80080
	v_lshl_add_u64 v[158:159], v[164:165], 0, s[6:7]
	s_addc_u32 s27, s27, 0
	s_add_i32 s28, s68, s38
	global_load_lds_dwordx4 v[158:159], off
	v_lshl_add_u64 v[158:159], s[26:27], 0, v[144:145]
	s_mov_b32 m0, s28
	s_nop 0
	global_load_lds_dwordx4 v[158:159], off
	v_lshl_add_u64 v[158:159], s[26:27], 0, v[146:147]
	s_add_i32 m0, s28, 0x2000
	s_nop 0
	global_load_lds_dwordx4 v[158:159], off
	v_lshl_add_u64 v[158:159], v[220:221], 0, s[6:7]
	s_mov_b32 m0, s48
	s_nop 0
	global_load_lds_dwordx4 v[158:159], off
	v_lshl_add_u64 v[158:159], v[222:223], 0, s[6:7]
	s_mov_b32 m0, s49
	s_nop 0
	global_load_lds_dwordx4 v[158:159], off
	s_waitcnt vmcnt(8)
	s_waitcnt lgkmcnt(0)
	s_barrier
	s_waitcnt lgkmcnt(0)
	v_mfma_f32_16x16x32_bf16 v[60:63], v[128:131], v[188:191], v[60:63]
	v_mfma_f32_16x16x32_bf16 v[56:59], v[136:139], v[188:191], v[56:59]
	v_mfma_f32_16x16x32_bf16 v[52:55], v[128:131], v[196:199], v[52:55]
	v_mfma_f32_16x16x32_bf16 v[48:51], v[136:139], v[196:199], v[48:51]
	v_mfma_f32_16x16x32_bf16 v[36:39], v[128:131], v[204:207], v[36:39]
	v_mfma_f32_16x16x32_bf16 v[24:27], v[136:139], v[204:207], v[24:27]
	v_mfma_f32_16x16x32_bf16 v[20:23], v[128:131], v[212:215], v[20:23]
	v_mfma_f32_16x16x32_bf16 v[8:11], v[136:139], v[212:215], v[8:11]
	v_mfma_f32_16x16x32_bf16 v[60:63], v[132:135], v[192:195], v[60:63]
	v_mfma_f32_16x16x32_bf16 v[56:59], v[140:143], v[192:195], v[56:59]
	v_mfma_f32_16x16x32_bf16 v[52:55], v[132:135], v[200:203], v[52:55]
	v_mfma_f32_16x16x32_bf16 v[48:51], v[140:143], v[200:203], v[48:51]
	v_mfma_f32_16x16x32_bf16 v[36:39], v[132:135], v[208:211], v[36:39]
	v_mfma_f32_16x16x32_bf16 v[24:27], v[140:143], v[208:211], v[24:27]
	v_mfma_f32_16x16x32_bf16 v[20:23], v[132:135], v[216:219], v[20:23]
	v_mfma_f32_16x16x32_bf16 v[8:11], v[140:143], v[216:219], v[8:11]
	v_mfma_f32_16x16x32_bf16 v[44:47], v[172:175], v[188:191], v[44:47]
	v_mfma_f32_16x16x32_bf16 v[40:43], v[180:183], v[188:191], v[40:43]
	v_mfma_f32_16x16x32_bf16 v[32:35], v[172:175], v[196:199], v[32:35]
	v_mfma_f32_16x16x32_bf16 v[28:31], v[180:183], v[196:199], v[28:31]
	v_mfma_f32_16x16x32_bf16 v[16:19], v[172:175], v[204:207], v[16:19]
	v_mfma_f32_16x16x32_bf16 v[12:15], v[180:183], v[204:207], v[12:15]
	v_mfma_f32_16x16x32_bf16 v[4:7], v[172:175], v[212:215], v[4:7]
	v_mfma_f32_16x16x32_bf16 v[0:3], v[180:183], v[212:215], v[0:3]
	v_mfma_f32_16x16x32_bf16 v[44:47], v[176:179], v[192:195], v[44:47]
	v_mfma_f32_16x16x32_bf16 v[40:43], v[184:187], v[192:195], v[40:43]
	v_mfma_f32_16x16x32_bf16 v[32:35], v[176:179], v[200:203], v[32:35]
	v_mfma_f32_16x16x32_bf16 v[28:31], v[184:187], v[200:203], v[28:31]
	v_mfma_f32_16x16x32_bf16 v[16:19], v[176:179], v[208:211], v[16:19]
	v_mfma_f32_16x16x32_bf16 v[12:15], v[184:187], v[208:211], v[12:15]
	v_mfma_f32_16x16x32_bf16 v[4:7], v[176:179], v[216:219], v[4:7]
	v_mfma_f32_16x16x32_bf16 v[0:3], v[184:187], v[216:219], v[0:3]
	s_barrier
	s_add_u32 s24, s24, 0x100
	s_addc_u32 s25, s25, 0
	s_add_u32 s64, s64, 0x100
	s_addc_u32 s65, s65, 0
	s_cmp_ge_i32 s66, s62
	s_mov_b32 s26, s66
	s_cbranch_scc0 .LBB0_731
	s_and_b64 vcc, exec, s[8:9]
	s_cbranch_vccz .LBB0_734
	s_barrier

; __device__ __forceinline__ unsigned xb_ld(unsigned* p)              { return __hip_atomic_load(p, __ATOMIC_RELAXED, __HIP_MEMORY_SCOPE_AGENT); }
; __device__ __forceinline__ void xcd_barrier_complete(unsigned* bar, unsigned x, unsigned& nloc, unsigned& nx) {
;     const unsigned G = gridDim.x * gridDim.y * gridDim.z;
;     unsigned sum, cnt, mine, sp = 0u;
;     for (;;) {
;         sum = 0u; cnt = 0u; mine = 0u;
; #pragma unroll
;         for (unsigned j = 0; j < 16; ++j) { const unsigned c = xb_ld(&bar[XB_XCNT(j)]); sum += c; cnt += (c > 0u) ? 1u : 0u; mine = (j == x) ? c : mine; }
; __device__ __forceinline__ void xcd_barrier(const XcdBarrier& b) {
;     asm volatile("s_waitcnt vmcnt(0)" ::: "memory");
;     __syncthreads();
;     if (threadIdx.x == 0) {
;         unsigned* bar = b.bar;
;         __builtin_amdgcn_s_waitcnt(0);
;         unsigned nloc = b.st[0], nx = b.st[1];
;         if (nloc == 0u) { xcd_barrier_complete(bar, b.x, nloc, nx); b.st[0] = nloc; b.st[1] = nx; }
.LBB0_745:
	s_setprio 0
	s_cmp_gt_i32 s81, 6
	s_cselect_b64 s[2:3], -1, 0
	s_and_b64 s[0:1], s[0:1], s[2:3]
	s_andn2_b64 vcc, exec, s[0:1]
	s_cbranch_vccnz .LBB0_799
	s_waitcnt vmcnt(0)
	s_waitcnt vmcnt(0)
	s_barrier
	s_and_saveexec_b64 s[0:1], s[94:95]
	s_cbranch_execz .LBB0_798
	s_add_i32 s4, 0, 0x23fc0
	v_mov_b32_e32 v0, s4
	s_waitcnt vmcnt(0) expcnt(0) lgkmcnt(0)
	ds_read_b32 v2, v0
	s_add_i32 s4, 0, 0x23fc4
	v_mov_b32_e32 v0, s4
	ds_read_b32 v0, v0
	s_waitcnt lgkmcnt(1)
	v_cmp_ne_u32_e32 vcc, 0, v2
	s_cbranch_vccnz .LBB0_762
	v_readlane_b32 s4, v241, 0
	s_mul_i32 s33, s83, s4
	s_add_u32 s4, s90, 0x88200
	s_addc_u32 s5, s91, 0
	s_add_u32 s6, s90, 0x88400
	s_addc_u32 s7, s91, 0
	s_add_u32 s8, s90, 0x88500
	s_addc_u32 s9, s91, 0
	s_add_u32 s10, s90, 0x88600
	s_addc_u32 s11, s91, 0
	s_add_u32 s12, s90, 0x88700
	s_addc_u32 s13, s91, 0
	s_add_u32 s14, s90, 0x88800
	s_addc_u32 s15, s91, 0
	s_add_u32 s16, s90, 0x88900
	s_addc_u32 s17, s91, 0
	s_add_u32 s18, s90, 0x88a00
	s_addc_u32 s19, s91, 0
	s_add_u32 s20, s90, 0x88b00
	s_addc_u32 s21, s91, 0
	s_add_u32 s22, s90, 0x88c00
	s_addc_u32 s23, s91, 0
	s_add_u32 s24, s90, 0x88d00
	s_addc_u32 s25, s91, 0
	s_add_u32 s26, s90, 0x88e00
	s_addc_u32 s27, s91, 0
	s_add_u32 s28, s90, 0x88f00
	s_addc_u32 s29, s91, 0
	s_add_u32 s30, s90, 0x89000
	s_addc_u32 s31, s91, 0
	s_add_u32 s34, s90, 0x89100
	s_addc_u32 s35, s91, 0
	s_add_u32 s36, s90, 0x89200
	s_addc_u32 s37, s91, 0
	s_add_u32 s38, s90, 0x89300
	s_mul_i32 s33, s33, s82
	s_addc_u32 s39, s91, 0
	s_mov_b32 s46, 1
	v_mov_b32_e32 v16, 0
	s_branch .LBB0_750

; #define PG8_STAGE(bufoff, gbase, voff) do { _Pragma("unroll") for (int _i = 0; _i < 2; ++_i) \
;         __builtin_amdgcn_global_load_lds((const unsigned*)((const char*)(gbase) + (voff)[_i]), (LAS unsigned*)(lds + (bufoff) + ldsw + _i * 8192), 16, 0, 0); } while (0)
; #define PG8_WAIT_V(n) asm volatile("s_waitcnt vmcnt(" #n ")" ::: "memory")
; #define PG8_BAR __builtin_amdgcn_s_barrier()
; template <class Epi, class Sched, bool ALIGN_EPI = false, bool SP2 = false>
; __device__ __forceinline__ void gemm_phase(LAS unsigned char* lds, const Gemm g, const Sched& S, const Epi& E) {
;     const int tid = threadIdx.x, wid = __builtin_amdgcn_readfirstlane(tid >> 6), lane = tid & 63, wr = wid >> 2, wc = wid & 3, fr = lane & 15, fq = lane >> 4;
;     const int K = g.ld;
;     unsigned voffA[2], voffB[2];
; #pragma unroll
;     for (int i = 0; i < 2; ++i) { int R, C; stage_rc(tid * 16 + i * 8192, R, C); const int Rb = Epi::PERM ? ((R & ~31) + perm32(R & 31)) : R;
;         voffA[i] = (unsigned)(R * K + C) * 2u; voffB[i] = (unsigned)(Rb * K + C) * 2u; }
;     const size_t kstep = (size_t)(BK * 2);
;     const size_t hstep = (size_t)HALF * K * 2;
;     const unsigned ldsw = (unsigned)wid * 1024u;
;     const int aoff = lds_byte(wr * 64 + fr, fq * 8), boff = lds_byte(wc * 32 + fr, fq * 8);
;     ...
;     Unit cur, nxt; int ui = 0;
;     if (!S.next(0, cur)) return;
;     f32x4 acc[2][2][4][2];
; #pragma unroll
;     for (int a = 0; a < 2; ++a)
; #pragma unroll
;         for (int b = 0; b < 2; ++b)
; #pragma unroll
;             for (int m = 0; m < 4; ++m)
; #pragma unroll
;                 for (int n = 0; n < 2; ++n) acc[a][b][m][n] = (f32x4){0.f, 0.f, 0.f, 0.f};
;     bf16x8 At[4][2], B0[2][2], B1[2][2];
;     const char* cA = cur.a; const char* cB = cur.b;
;     S.a_ready(cur);
;     if constexpr (SP2) {
;         PG8_STAGE(PG8_SB(0, 0), cB, voffB); PG8_STAGE(PG8_SB(0, 1), cB + hstep, voffB); PG8_STAGE(PG8_SA(0, 0), cA, voffA); PG8_STAGE(PG8_SA(0, 1), cA + hstep, voffA);
;         if (wr == 1) PG8_BAR;
;         PG8_WAIT_V(2); PG8_BAR;
.LBB0_882:
	s_cmp_lt_i32 s80, 8
	s_cselect_b64 s[2:3], -1, 0
	s_and_b64 s[2:3], s[2:3], s[0:1]
	s_andn2_b64 vcc, exec, s[2:3]
	s_cbranch_vccnz .LBB0_899
	v_readfirstlane_b32 s101, v162
	s_nop 3
	s_lshr_b32 s101, s101, 6
	s_cmp_ge_u32 s101, 4
	s_cbranch_scc0 .Lsp_20293
	s_setprio 1
.Lsp_20293:
	s_cmpk_gt_i32 s92, 0x87f
	v_readfirstlane_b32 s1, v162
	s_cbranch_scc1 .LBB0_899
	v_lshrrev_b32_e32 v2, 1, v162
	v_and_b32_e32 v11, 24, v2
	v_lshrrev_b32_e32 v2, 5, v162
	v_and_b32_e32 v2, 4, v2
	v_bfe_u32 v3, v162, 2, 2
	s_add_u32 s33, s90, 0xc600000
	v_lshlrev_b32_e32 v0, 4, v162
	v_and_b32_e32 v1, 32, v162
	v_bfe_u32 v10, v162, 2, 4
	v_or3_b32 v2, v2, v3, v11
	v_lshrrev_b32_e32 v3, 3, v162
	s_movk_i32 s0, 0x70
	s_addc_u32 s44, s91, 0
	v_bitop3_b32 v8, v0, v1, 48 bitop3:0x6c
	v_and_b32_e32 v9, 64, v162
	v_and_or_b32 v4, v3, s0, v10
	s_movk_i32 s0, 0x60
	v_add_u32_e32 v12, 0x2000, v0
	s_add_u32 s45, s90, 0x1e00000
	v_or_b32_e32 v1, v8, v9
	v_and_or_b32 v3, v3, s0, v2
	v_lshrrev_b32_e32 v0, 7, v12
	s_movk_i32 s0, 0xf0
	s_addc_u32 s46, s91, 0
	v_lshl_or_b32 v130, v3, 12, v1
	v_and_or_b32 v3, v0, s0, v10
	s_movk_i32 s0, 0xe0
	s_ashr_i32 s48, s92, 31
	v_and_or_b32 v0, v0, s0, v2
	s_lshr_b32 s0, s48, 29
	s_add_i32 s0, s92, s0
	s_lshr_b32 s8, s1, 6
	s_ashr_i32 s6, s0, 3
	s_and_b32 s0, s0, -8
	s_lshr_b32 s10, s1, 8
	s_lshl_b32 s47, s8, 10
	s_sub_i32 s0, s92, s0
	s_cmp_lt_i32 s0, 0
	s_movk_i32 s49, 0x111
	s_cselect_b32 s7, s49, 0x110
	s_mul_i32 s0, s0, s7
	s_add_i32 s0, s0, s6
	s_ashr_i32 s6, s0, 31
	s_lshr_b32 s6, s6, 25
	s_add_i32 s6, s0, s6
	s_ashr_i32 s7, s6, 7
	s_and_b32 s6, s6, 0xff80
	s_sub_i32 s0, s0, s6
	s_bfe_i32 s6, s0, 0x80000
	s_bfe_u32 s6, s6, 0x2000d
	s_add_i32 s6, s0, s6
	s_and_b32 s9, s6, 0xfc
	s_sub_i32 s0, s0, s9
	s_lshl_b32 s7, s7, 2
	s_sext_i32_i8 s0, s0
	s_add_i32 s30, s7, s0
	s_bfe_i32 s0, s6, 0x80000
	s_sext_i32_i16 s0, s0
	s_ashr_i32 s31, s30, 31
	s_lshr_b32 s0, s0, 2
	s_lshl_b64 s[6:7], s[30:31], 20
	s_add_u32 s38, s33, s6
	s_addc_u32 s39, s44, s7
	s_bfe_i64 s[6:7], s[0:1], 0x100000
	s_lshl_b64 s[6:7], s[6:7], 20
	s_add_u32 s40, s45, s6
	s_addc_u32 s41, s46, s7
	s_add_i32 s31, s47, 0
	s_add_i32 m0, s31, 0x10000
	v_lshl_or_b32 v134, v0, 12, v1
	global_load_lds_dwordx4 v130, s[40:41]
	s_add_i32 m0, s31, 0x12000
	s_add_u32 s6, s40, 0x80000
	global_load_lds_dwordx4 v134, s[40:41]
	s_addc_u32 s7, s41, 0
	s_add_i32 m0, s31, 0x14000
	s_add_i32 s50, s31, 0x2000
	global_load_lds_dwordx4 v130, s[6:7]
	s_add_i32 m0, s31, 0x16000
	v_lshl_or_b32 v128, v4, 12, v1
	global_load_lds_dwordx4 v134, s[6:7]
	s_mov_b32 m0, s31
	s_add_u32 s6, s38, 0x80000
	v_lshl_or_b32 v132, v3, 12, v1
	global_load_lds_dwordx4 v128, s[38:39]
	s_mov_b32 m0, s50
	s_addc_u32 s7, s39, 0
	s_add_i32 s51, s31, 0x4000
	global_load_lds_dwordx4 v132, s[38:39]
	s_mov_b32 m0, s51
	s_add_i32 s52, s31, 0x6000
	global_load_lds_dwordx4 v128, s[6:7]
	s_mov_b32 m0, s52
	v_mov_b32_e32 v131, 0
	global_load_lds_dwordx4 v132, s[6:7]
	v_mov_b32_e32 v135, v131
	v_mov_b32_e32 v129, v131
	v_mov_b32_e32 v133, v131
	s_cmp_eq_u32 s10, 1
	s_mov_b32 s53, 0
	v_lshl_add_u64 v[6:7], s[40:41], 0, v[130:131]
	v_lshl_add_u64 v[4:5], s[40:41], 0, v[134:135]
	v_lshl_add_u64 v[0:1], s[38:39], 0, v[128:129]
	s_cselect_b64 s[6:7], -1, 0
	s_cmp_lg_u32 s10, 1
	v_lshl_add_u64 v[2:3], s[38:39], 0, v[132:133]
	s_cbranch_scc1 .LBB0_886
	s_barrier

; #define PG8_STAGE(bufoff, gbase, voff) do { _Pragma("unroll") for (int _i = 0; _i < 2; ++_i) \
;         __builtin_amdgcn_global_load_lds((const unsigned*)((const char*)(gbase) + (voff)[_i]), (LAS unsigned*)(lds + (bufoff) + ldsw + _i * 8192), 16, 0, 0); } while (0)
; #define PG8_LDA(dst, b, h) do { _Pragma("unroll") for (int m = 0; m < 4; ++m) _Pragma("unroll") for (int k = 0; k < 2; ++k) dst[m][k] = *(const LAS bf16x8*)(lds + PG8_SA(b, h) + aoff + m * 2048 + k * 1024); } while (0)
; #define PG8_LDB(dst, b, h) do { _Pragma("unroll") for (int n = 0; n < 2; ++n) _Pragma("unroll") for (int k = 0; k < 2; ++k) dst[n][k] = *(const LAS bf16x8*)(lds + PG8_SB(b, h) + boff + n * 2048 + k * 1024); } while (0)
; #define PG8_MMA(ai, bj, At, Bt) do { __builtin_amdgcn_s_setprio(1); _Pragma("unroll") for (int m = 0; m < 4; ++m) _Pragma("unroll") for (int n = 0; n < 2; ++n) _Pragma("unroll") for (int k = 0; k < 2; ++k) \
;         acc[ai][bj][m][n] = __builtin_amdgcn_mfma_f32_16x16x32_bf16(Bt[n][k], At[m][k], acc[ai][bj][m][n], 0, 0, 0); __builtin_amdgcn_s_setprio(0); } while (0)
; #define PG8_WAIT_V(n) asm volatile("s_waitcnt vmcnt(" #n ")" ::: "memory")
; #define PG8_WAIT_L(n) asm volatile("s_waitcnt lgkmcnt(" #n ")" ::: "memory")
; #define PG8_BAR __builtin_amdgcn_s_barrier()
; template <class Epi, class Sched, bool ALIGN_EPI = false, bool SP2 = false>
; __device__ __forceinline__ void gemm_phase(LAS unsigned char* lds, const Gemm g, const Sched& S, const Epi& E) {
;     ...
;             const bool last = (t == nt - 2);
;             const char* a1 = cA + (size_t)(t + 1) * kstep;
;             const char* a2 = last ? nA : cA + (size_t)(t + 2) * kstep; const char* b2 = last ? nB : cB + (size_t)(t + 2) * kstep;
;             const char* a3 = a2 + kstep; const char* b3 = b2 + kstep;
;             if (last && has_next) S.a_ready(nxt);
;             if constexpr (SP2) {
;             PG8_LDB(B0, 0, 0); PG8_LDB(B1, 0, 1); PG8_SCHED; PG8_LDA(At, 0, 0); PG8_STAGE(PG8_SA(1, 1), a1 + hstep, voffA);
;             PG8_WAIT_V(8); PG8_WAIT_L(0); PG8_BAR; PG8_MMA(0, 0, At, B0); PG8_MMA(0, 1, At, B1); PG8_BAR; PG8_SCHED;
;             PG8_LDA(At, 0, 1); PG8_STAGE(PG8_SB(0, 0), b2, voffB); PG8_STAGE(PG8_SB(0, 1), b2 + hstep, voffB); PG8_STAGE(PG8_SA(0, 0), a2, voffA);
;             PG8_WAIT_V(8); PG8_WAIT_L(0); PG8_BAR; PG8_MMA(1, 0, At, B0); PG8_MMA(1, 1, At, B1); PG8_BAR; PG8_SCHED;
.LBB0_892:
	ds_read_b128 v[152:155], v149
	ds_read_b128 v[156:159], v149 offset:1024
	ds_read_b128 v[164:167], v149 offset:2048
	ds_read_b128 v[170:173], v149 offset:3072
	ds_read_b128 v[174:177], v150
	ds_read_b128 v[178:181], v150 offset:1024
	ds_read_b128 v[182:185], v150 offset:2048
	ds_read_b128 v[186:189], v150 offset:3072
	s_add_u32 s40, s38, 0xfff80080
	s_addc_u32 s41, s39, -1
	s_cmp_eq_u32 s65, 28
	s_cselect_b32 s43, s35, s41
	s_cselect_b32 s42, s34, s40
	s_cselect_b32 s41, s37, s25
	s_cselect_b32 s40, s36, s23
	v_lshl_add_u64 v[144:145], s[38:39], 0, v[136:137]
	s_add_i32 m0, s31, 0xc000
	ds_read_b128 v[190:193], v151
	ds_read_b128 v[194:197], v151 offset:1024
	ds_read_b128 v[198:201], v151 offset:2048
	ds_read_b128 v[202:205], v151 offset:3072
	ds_read_b128 v[206:209], v151 offset:4096
	ds_read_b128 v[210:213], v151 offset:5120
	ds_read_b128 v[214:217], v151 offset:6144
	ds_read_b128 v[218:221], v151 offset:7168
	global_load_lds_dwordx4 v[144:145], off
	v_lshl_add_u64 v[144:145], s[38:39], 0, v[138:139]
	s_add_i32 m0, s31, 0xe000
	s_nop 0
	global_load_lds_dwordx4 v[144:145], off
	s_waitcnt vmcnt(8)
	s_waitcnt lgkmcnt(0)
	s_barrier
	s_waitcnt lgkmcnt(0)
	v_mfma_f32_16x16x32_bf16 v[124:127], v[152:155], v[190:193], v[124:127]
	v_mfma_f32_16x16x32_bf16 v[120:123], v[164:167], v[190:193], v[120:123]
	v_mfma_f32_16x16x32_bf16 v[108:111], v[152:155], v[198:201], v[108:111]
	v_mfma_f32_16x16x32_bf16 v[104:107], v[164:167], v[198:201], v[104:107]
	v_mfma_f32_16x16x32_bf16 v[92:95], v[152:155], v[206:209], v[92:95]
	v_mfma_f32_16x16x32_bf16 v[88:91], v[164:167], v[206:209], v[88:91]
	v_mfma_f32_16x16x32_bf16 v[76:79], v[152:155], v[214:217], v[76:79]
	v_mfma_f32_16x16x32_bf16 v[72:75], v[164:167], v[214:217], v[72:75]
	v_mfma_f32_16x16x32_bf16 v[124:127], v[156:159], v[194:197], v[124:127]
	v_mfma_f32_16x16x32_bf16 v[120:123], v[170:173], v[194:197], v[120:123]
	v_mfma_f32_16x16x32_bf16 v[108:111], v[156:159], v[202:205], v[108:111]
	v_mfma_f32_16x16x32_bf16 v[104:107], v[170:173], v[202:205], v[104:107]
	v_mfma_f32_16x16x32_bf16 v[92:95], v[156:159], v[210:213], v[92:95]
	v_mfma_f32_16x16x32_bf16 v[88:91], v[170:173], v[210:213], v[88:91]
	v_mfma_f32_16x16x32_bf16 v[76:79], v[156:159], v[218:221], v[76:79]
	v_mfma_f32_16x16x32_bf16 v[72:75], v[170:173], v[218:221], v[72:75]
	v_mfma_f32_16x16x32_bf16 v[116:119], v[174:177], v[190:193], v[116:119]
	v_mfma_f32_16x16x32_bf16 v[112:115], v[182:185], v[190:193], v[112:115]
	v_mfma_f32_16x16x32_bf16 v[100:103], v[174:177], v[198:201], v[100:103]
	v_mfma_f32_16x16x32_bf16 v[96:99], v[182:185], v[198:201], v[96:99]
	v_mfma_f32_16x16x32_bf16 v[84:87], v[174:177], v[206:209], v[84:87]
	v_mfma_f32_16x16x32_bf16 v[80:83], v[182:185], v[206:209], v[80:83]
	v_mfma_f32_16x16x32_bf16 v[68:71], v[174:177], v[214:217], v[68:71]
	v_mfma_f32_16x16x32_bf16 v[64:67], v[182:185], v[214:217], v[64:67]
	v_mfma_f32_16x16x32_bf16 v[116:119], v[178:181], v[194:197], v[116:119]
	v_mfma_f32_16x16x32_bf16 v[112:115], v[186:189], v[194:197], v[112:115]
	v_mfma_f32_16x16x32_bf16 v[100:103], v[178:181], v[202:205], v[100:103]
	v_mfma_f32_16x16x32_bf16 v[96:99], v[186:189], v[202:205], v[96:99]
	v_mfma_f32_16x16x32_bf16 v[84:87], v[178:181], v[210:213], v[84:87]
	v_mfma_f32_16x16x32_bf16 v[80:83], v[186:189], v[210:213], v[80:83]
	v_mfma_f32_16x16x32_bf16 v[68:71], v[178:181], v[218:221], v[68:71]
	v_mfma_f32_16x16x32_bf16 v[64:67], v[186:189], v[218:221], v[64:67]
	s_barrier
	s_add_i32 s66, s58, s47
	v_lshl_add_u64 v[144:145], s[40:41], 0, v[130:131]
	s_mov_b32 m0, s66
	ds_read_b128 v[190:193], v151 offset:16384
	ds_read_b128 v[194:197], v151 offset:17408
	ds_read_b128 v[198:201], v151 offset:18432
	ds_read_b128 v[202:205], v151 offset:19456
	ds_read_b128 v[206:209], v151 offset:20480
	ds_read_b128 v[210:213], v151 offset:21504
	ds_read_b128 v[214:217], v151 offset:22528
	ds_read_b128 v[218:221], v151 offset:23552
	global_load_lds_dwordx4 v[144:145], off
	s_add_i32 m0, s66, 0x2000
	s_add_u32 s66, s40, 0x80000
	v_lshl_add_u64 v[222:223], s[40:41], 0, v[134:135]
	s_addc_u32 s67, s41, 0
	s_add_i32 s68, s59, s47
	global_load_lds_dwordx4 v[222:223], off
	v_lshl_add_u64 v[224:225], s[66:67], 0, v[130:131]
	s_mov_b32 m0, s68
	v_lshl_add_u64 v[226:227], s[42:43], 0, v[132:133]
	global_load_lds_dwordx4 v[224:225], off
	v_lshl_add_u64 v[224:225], s[66:67], 0, v[134:135]
	s_add_i32 m0, s68, 0x2000
	s_nop 0
	global_load_lds_dwordx4 v[224:225], off
	v_lshl_add_u64 v[224:225], s[42:43], 0, v[128:129]
	s_mov_b32 m0, s31
	s_nop 0
	global_load_lds_dwordx4 v[224:225], off
	s_mov_b32 m0, s50
	s_nop 0
	global_load_lds_dwordx4 v[226:227], off
	s_waitcnt vmcnt(8)
	s_waitcnt lgkmcnt(0)
	s_barrier
; #define PG8_STAGE(bufoff, gbase, voff) do { _Pragma("unroll") for (int _i = 0; _i < 2; ++_i) \
;         __builtin_amdgcn_global_load_lds((const unsigned*)((const char*)(gbase) + (voff)[_i]), (LAS unsigned*)(lds + (bufoff) + ldsw + _i * 8192), 16, 0, 0); } while (0)
; #define PG8_LDA(dst, b, h) do { _Pragma("unroll") for (int m = 0; m < 4; ++m) _Pragma("unroll") for (int k = 0; k < 2; ++k) dst[m][k] = *(const LAS bf16x8*)(lds + PG8_SA(b, h) + aoff + m * 2048 + k * 1024); } while (0)
; #define PG8_LDB(dst, b, h) do { _Pragma("unroll") for (int n = 0; n < 2; ++n) _Pragma("unroll") for (int k = 0; k < 2; ++k) dst[n][k] = *(const LAS bf16x8*)(lds + PG8_SB(b, h) + boff + n * 2048 + k * 1024); } while (0)
; #define PG8_MMA(ai, bj, At, Bt) do { __builtin_amdgcn_s_setprio(1); _Pragma("unroll") for (int m = 0; m < 4; ++m) _Pragma("unroll") for (int n = 0; n < 2; ++n) _Pragma("unroll") for (int k = 0; k < 2; ++k) \
;         acc[ai][bj][m][n] = __builtin_amdgcn_mfma_f32_16x16x32_bf16(Bt[n][k], At[m][k], acc[ai][bj][m][n], 0, 0, 0); __builtin_amdgcn_s_setprio(0); } while (0)
; #define PG8_WAIT_V(n) asm volatile("s_waitcnt vmcnt(" #n ")" ::: "memory")
; #define PG8_WAIT_L(n) asm volatile("s_waitcnt lgkmcnt(" #n ")" ::: "memory")
; #define PG8_BAR __builtin_amdgcn_s_barrier()
; #define PG8_SCHED __builtin_amdgcn_sched_barrier(0)
; template <class Epi, class Sched, bool ALIGN_EPI = false, bool SP2 = false>
; __device__ __forceinline__ void gemm_phase(LAS unsigned char* lds, const Gemm g, const Sched& S, const Epi& E) {
;     ...
;             PG8_WAIT_V(8); PG8_WAIT_L(0); PG8_BAR; PG8_MMA(1, 0, At, B0); PG8_MMA(1, 1, At, B1); PG8_BAR; PG8_SCHED;
;             PG8_LDB(B0, 1, 0); PG8_LDB(B1, 1, 1); PG8_SCHED; PG8_LDA(At, 1, 0); PG8_STAGE(PG8_SA(0, 1), a2 + hstep, voffA);
;             PG8_WAIT_V(8); PG8_WAIT_L(0); PG8_BAR; PG8_MMA(0, 0, At, B0); PG8_MMA(0, 1, At, B1); PG8_BAR; PG8_SCHED;
	s_waitcnt lgkmcnt(0)
	v_mfma_f32_16x16x32_bf16 v[60:63], v[152:155], v[190:193], v[60:63]
	v_mfma_f32_16x16x32_bf16 v[56:59], v[164:167], v[190:193], v[56:59]
	v_mfma_f32_16x16x32_bf16 v[44:47], v[152:155], v[198:201], v[44:47]
	v_mfma_f32_16x16x32_bf16 v[40:43], v[164:167], v[198:201], v[40:43]
	v_mfma_f32_16x16x32_bf16 v[28:31], v[152:155], v[206:209], v[28:31]
	v_mfma_f32_16x16x32_bf16 v[24:27], v[164:167], v[206:209], v[24:27]
	v_mfma_f32_16x16x32_bf16 v[12:15], v[152:155], v[214:217], v[12:15]
	v_mfma_f32_16x16x32_bf16 v[8:11], v[164:167], v[214:217], v[8:11]
	v_mfma_f32_16x16x32_bf16 v[60:63], v[156:159], v[194:197], v[60:63]
	v_mfma_f32_16x16x32_bf16 v[56:59], v[170:173], v[194:197], v[56:59]
	v_mfma_f32_16x16x32_bf16 v[44:47], v[156:159], v[202:205], v[44:47]
	v_mfma_f32_16x16x32_bf16 v[40:43], v[170:173], v[202:205], v[40:43]
	v_mfma_f32_16x16x32_bf16 v[28:31], v[156:159], v[210:213], v[28:31]
	v_mfma_f32_16x16x32_bf16 v[24:27], v[170:173], v[210:213], v[24:27]
	v_mfma_f32_16x16x32_bf16 v[12:15], v[156:159], v[218:221], v[12:15]
	v_mfma_f32_16x16x32_bf16 v[8:11], v[170:173], v[218:221], v[8:11]
	v_mfma_f32_16x16x32_bf16 v[52:55], v[174:177], v[190:193], v[52:55]
	v_mfma_f32_16x16x32_bf16 v[48:51], v[182:185], v[190:193], v[48:51]
	v_mfma_f32_16x16x32_bf16 v[36:39], v[174:177], v[198:201], v[36:39]
	v_mfma_f32_16x16x32_bf16 v[32:35], v[182:185], v[198:201], v[32:35]
	v_mfma_f32_16x16x32_bf16 v[20:23], v[174:177], v[206:209], v[20:23]
	v_mfma_f32_16x16x32_bf16 v[16:19], v[182:185], v[206:209], v[16:19]
	v_mfma_f32_16x16x32_bf16 v[4:7], v[174:177], v[214:217], v[4:7]
	v_mfma_f32_16x16x32_bf16 v[0:3], v[182:185], v[214:217], v[0:3]
	v_mfma_f32_16x16x32_bf16 v[52:55], v[178:181], v[194:197], v[52:55]
	v_mfma_f32_16x16x32_bf16 v[48:51], v[186:189], v[194:197], v[48:51]
	v_mfma_f32_16x16x32_bf16 v[36:39], v[178:181], v[202:205], v[36:39]
	v_mfma_f32_16x16x32_bf16 v[32:35], v[186:189], v[202:205], v[32:35]
	v_mfma_f32_16x16x32_bf16 v[20:23], v[178:181], v[210:213], v[20:23]
	v_mfma_f32_16x16x32_bf16 v[16:19], v[186:189], v[210:213], v[16:19]
	v_mfma_f32_16x16x32_bf16 v[4:7], v[178:181], v[218:221], v[4:7]
	v_mfma_f32_16x16x32_bf16 v[0:3], v[186:189], v[218:221], v[0:3]
	s_barrier
	s_add_i32 s66, 0, 0x18000
	v_add_u32_e32 v163, s66, v147
	s_add_i32 s67, 0, 0x1c000
	ds_read_b128 v[152:155], v163
	ds_read_b128 v[156:159], v163 offset:1024
	ds_read_b128 v[164:167], v163 offset:2048
	ds_read_b128 v[170:173], v163 offset:3072
	v_add_u32_e32 v163, s67, v147
	ds_read_b128 v[174:177], v163
	ds_read_b128 v[178:181], v163 offset:1024
	ds_read_b128 v[182:185], v163 offset:2048
	ds_read_b128 v[186:189], v163 offset:3072
	s_add_u32 s42, s42, 0x80000
	s_addc_u32 s43, s43, 0
	s_mov_b32 m0, s51
	v_lshl_add_u64 v[228:229], s[42:43], 0, v[128:129]
	ds_read_b128 v[190:193], v151 offset:32768
	ds_read_b128 v[194:197], v151 offset:33792
	ds_read_b128 v[198:201], v151 offset:34816
	ds_read_b128 v[202:205], v151 offset:35840
	ds_read_b128 v[206:209], v151 offset:36864
	ds_read_b128 v[210:213], v151 offset:37888
	ds_read_b128 v[214:217], v151 offset:38912
	ds_read_b128 v[218:221], v151 offset:39936
	global_load_lds_dwordx4 v[228:229], off
	v_lshl_add_u64 v[228:229], s[42:43], 0, v[132:133]
	s_mov_b32 m0, s52
	s_nop 0
	global_load_lds_dwordx4 v[228:229], off
	s_waitcnt vmcnt(8)
	s_waitcnt lgkmcnt(0)
	s_barrier
	s_waitcnt lgkmcnt(0)
	v_mfma_f32_16x16x32_bf16 v[124:127], v[152:155], v[190:193], v[124:127]
	v_mfma_f32_16x16x32_bf16 v[120:123], v[164:167], v[190:193], v[120:123]
	v_mfma_f32_16x16x32_bf16 v[108:111], v[152:155], v[198:201], v[108:111]
	v_mfma_f32_16x16x32_bf16 v[104:107], v[164:167], v[198:201], v[104:107]
	v_mfma_f32_16x16x32_bf16 v[92:95], v[152:155], v[206:209], v[92:95]
	v_mfma_f32_16x16x32_bf16 v[88:91], v[164:167], v[206:209], v[88:91]
	v_mfma_f32_16x16x32_bf16 v[76:79], v[152:155], v[214:217], v[76:79]
	v_mfma_f32_16x16x32_bf16 v[72:75], v[164:167], v[214:217], v[72:75]
	v_mfma_f32_16x16x32_bf16 v[124:127], v[156:159], v[194:197], v[124:127]
	v_mfma_f32_16x16x32_bf16 v[120:123], v[170:173], v[194:197], v[120:123]
	v_mfma_f32_16x16x32_bf16 v[108:111], v[156:159], v[202:205], v[108:111]
	v_mfma_f32_16x16x32_bf16 v[104:107], v[170:173], v[202:205], v[104:107]
	v_mfma_f32_16x16x32_bf16 v[92:95], v[156:159], v[210:213], v[92:95]
	v_mfma_f32_16x16x32_bf16 v[88:91], v[170:173], v[210:213], v[88:91]
	v_mfma_f32_16x16x32_bf16 v[76:79], v[156:159], v[218:221], v[76:79]
	v_mfma_f32_16x16x32_bf16 v[72:75], v[170:173], v[218:221], v[72:75]
	v_mfma_f32_16x16x32_bf16 v[116:119], v[174:177], v[190:193], v[116:119]
	v_mfma_f32_16x16x32_bf16 v[112:115], v[182:185], v[190:193], v[112:115]
	v_mfma_f32_16x16x32_bf16 v[100:103], v[174:177], v[198:201], v[100:103]
	v_mfma_f32_16x16x32_bf16 v[96:99], v[182:185], v[198:201], v[96:99]
	v_mfma_f32_16x16x32_bf16 v[84:87], v[174:177], v[206:209], v[84:87]
	v_mfma_f32_16x16x32_bf16 v[80:83], v[182:185], v[206:209], v[80:83]
	v_mfma_f32_16x16x32_bf16 v[68:71], v[174:177], v[214:217], v[68:71]
	v_mfma_f32_16x16x32_bf16 v[64:67], v[182:185], v[214:217], v[64:67]
	v_mfma_f32_16x16x32_bf16 v[116:119], v[178:181], v[194:197], v[116:119]
	v_mfma_f32_16x16x32_bf16 v[112:115], v[186:189], v[194:197], v[112:115]
	v_mfma_f32_16x16x32_bf16 v[100:103], v[178:181], v[202:205], v[100:103]
	v_mfma_f32_16x16x32_bf16 v[96:99], v[186:189], v[202:205], v[96:99]
	v_mfma_f32_16x16x32_bf16 v[84:87], v[178:181], v[210:213], v[84:87]
	v_mfma_f32_16x16x32_bf16 v[80:83], v[186:189], v[210:213], v[80:83]
	v_mfma_f32_16x16x32_bf16 v[68:71], v[178:181], v[218:221], v[68:71]
	v_mfma_f32_16x16x32_bf16 v[64:67], v[186:189], v[218:221], v[64:67]
	s_barrier
; #define PG8_STAGE(bufoff, gbase, voff) do { _Pragma("unroll") for (int _i = 0; _i < 2; ++_i) \
;         __builtin_amdgcn_global_load_lds((const unsigned*)((const char*)(gbase) + (voff)[_i]), (LAS unsigned*)(lds + (bufoff) + ldsw + _i * 8192), 16, 0, 0); } while (0)
; #define PG8_LDA(dst, b, h) do { _Pragma("unroll") for (int m = 0; m < 4; ++m) _Pragma("unroll") for (int k = 0; k < 2; ++k) dst[m][k] = *(const LAS bf16x8*)(lds + PG8_SA(b, h) + aoff + m * 2048 + k * 1024); } while (0)
; #define PG8_MMA(ai, bj, At, Bt) do { __builtin_amdgcn_s_setprio(1); _Pragma("unroll") for (int m = 0; m < 4; ++m) _Pragma("unroll") for (int n = 0; n < 2; ++n) _Pragma("unroll") for (int k = 0; k < 2; ++k) \
;         acc[ai][bj][m][n] = __builtin_amdgcn_mfma_f32_16x16x32_bf16(Bt[n][k], At[m][k], acc[ai][bj][m][n], 0, 0, 0); __builtin_amdgcn_s_setprio(0); } while (0)
; #define PG8_WAIT_V(n) asm volatile("s_waitcnt vmcnt(" #n ")" ::: "memory")
; #define PG8_WAIT_L(n) asm volatile("s_waitcnt lgkmcnt(" #n ")" ::: "memory")
; #define PG8_BAR __builtin_amdgcn_s_barrier()
; #define PG8_SCHED __builtin_amdgcn_sched_barrier(0)
; template <class Epi, class Sched, bool ALIGN_EPI = false, bool SP2 = false>
; __device__ __forceinline__ void gemm_phase(LAS unsigned char* lds, const Gemm g, const Sched& S, const Epi& E) {
;     ...
;             PG8_LDA(At, 1, 1); PG8_STAGE(PG8_SB(1, 0), b3, voffB); PG8_STAGE(PG8_SB(1, 1), b3 + hstep, voffB); PG8_STAGE(PG8_SA(1, 0), a3, voffA);
;             PG8_WAIT_V(8); PG8_WAIT_L(0); PG8_BAR; PG8_MMA(1, 0, At, B0); PG8_MMA(1, 1, At, B1); PG8_BAR; PG8_SCHED;
	s_add_i32 s42, s66, s47
	v_lshl_add_u64 v[144:145], v[144:145], 0, s[8:9]
	s_mov_b32 m0, s42
	ds_read_b128 v[190:193], v151 offset:49152
	ds_read_b128 v[194:197], v151 offset:50176
	ds_read_b128 v[198:201], v151 offset:51200
	ds_read_b128 v[202:205], v151 offset:52224
	ds_read_b128 v[206:209], v151 offset:53248
	ds_read_b128 v[210:213], v151 offset:54272
	ds_read_b128 v[214:217], v151 offset:55296
	ds_read_b128 v[218:221], v151 offset:56320
	global_load_lds_dwordx4 v[144:145], off
	s_add_i32 m0, s42, 0x2000
	s_add_u32 s40, s40, 0x80080
	v_lshl_add_u64 v[144:145], v[222:223], 0, s[8:9]
	s_addc_u32 s41, s41, 0
	s_add_i32 s42, s67, s47
	global_load_lds_dwordx4 v[144:145], off
	v_lshl_add_u64 v[144:145], s[40:41], 0, v[130:131]
	s_mov_b32 m0, s42
	s_nop 0
	global_load_lds_dwordx4 v[144:145], off
	v_lshl_add_u64 v[144:145], s[40:41], 0, v[134:135]
	s_add_i32 m0, s42, 0x2000
	s_nop 0
	global_load_lds_dwordx4 v[144:145], off
	v_lshl_add_u64 v[144:145], v[224:225], 0, s[8:9]
	s_mov_b32 m0, s55
	s_nop 0
	global_load_lds_dwordx4 v[144:145], off
	v_lshl_add_u64 v[144:145], v[226:227], 0, s[8:9]
	s_mov_b32 m0, s56
	s_nop 0
	global_load_lds_dwordx4 v[144:145], off
	s_waitcnt vmcnt(8)
	s_waitcnt lgkmcnt(0)
	s_barrier
	s_waitcnt lgkmcnt(0)
	v_mfma_f32_16x16x32_bf16 v[60:63], v[152:155], v[190:193], v[60:63]
	v_mfma_f32_16x16x32_bf16 v[56:59], v[164:167], v[190:193], v[56:59]
	v_mfma_f32_16x16x32_bf16 v[44:47], v[152:155], v[198:201], v[44:47]
	v_mfma_f32_16x16x32_bf16 v[40:43], v[164:167], v[198:201], v[40:43]
	v_mfma_f32_16x16x32_bf16 v[28:31], v[152:155], v[206:209], v[28:31]
	v_mfma_f32_16x16x32_bf16 v[24:27], v[164:167], v[206:209], v[24:27]
	v_mfma_f32_16x16x32_bf16 v[12:15], v[152:155], v[214:217], v[12:15]
	v_mfma_f32_16x16x32_bf16 v[8:11], v[164:167], v[214:217], v[8:11]
	v_mfma_f32_16x16x32_bf16 v[60:63], v[156:159], v[194:197], v[60:63]
	v_mfma_f32_16x16x32_bf16 v[56:59], v[170:173], v[194:197], v[56:59]
	v_mfma_f32_16x16x32_bf16 v[44:47], v[156:159], v[202:205], v[44:47]
	v_mfma_f32_16x16x32_bf16 v[40:43], v[170:173], v[202:205], v[40:43]
	v_mfma_f32_16x16x32_bf16 v[28:31], v[156:159], v[210:213], v[28:31]
	v_mfma_f32_16x16x32_bf16 v[24:27], v[170:173], v[210:213], v[24:27]
	v_mfma_f32_16x16x32_bf16 v[12:15], v[156:159], v[218:221], v[12:15]
	v_mfma_f32_16x16x32_bf16 v[8:11], v[170:173], v[218:221], v[8:11]
	v_mfma_f32_16x16x32_bf16 v[52:55], v[174:177], v[190:193], v[52:55]
	v_mfma_f32_16x16x32_bf16 v[48:51], v[182:185], v[190:193], v[48:51]
	v_mfma_f32_16x16x32_bf16 v[36:39], v[174:177], v[198:201], v[36:39]
	v_mfma_f32_16x16x32_bf16 v[32:35], v[182:185], v[198:201], v[32:35]
	v_mfma_f32_16x16x32_bf16 v[20:23], v[174:177], v[206:209], v[20:23]
	v_mfma_f32_16x16x32_bf16 v[16:19], v[182:185], v[206:209], v[16:19]
	v_mfma_f32_16x16x32_bf16 v[4:7], v[174:177], v[214:217], v[4:7]
	v_mfma_f32_16x16x32_bf16 v[0:3], v[182:185], v[214:217], v[0:3]
	v_mfma_f32_16x16x32_bf16 v[52:55], v[178:181], v[194:197], v[52:55]
	v_mfma_f32_16x16x32_bf16 v[48:51], v[186:189], v[194:197], v[48:51]
	v_mfma_f32_16x16x32_bf16 v[36:39], v[178:181], v[202:205], v[36:39]
	v_mfma_f32_16x16x32_bf16 v[32:35], v[186:189], v[202:205], v[32:35]
	v_mfma_f32_16x16x32_bf16 v[20:23], v[178:181], v[210:213], v[20:23]
	v_mfma_f32_16x16x32_bf16 v[16:19], v[186:189], v[210:213], v[16:19]
	v_mfma_f32_16x16x32_bf16 v[4:7], v[178:181], v[218:221], v[4:7]
	v_mfma_f32_16x16x32_bf16 v[0:3], v[186:189], v[218:221], v[0:3]
	s_barrier
	s_add_i32 s65, s65, 2
	s_add_u32 s38, s38, 0x100
	s_addc_u32 s39, s39, 0
	s_add_u32 s23, s23, 0x100
	s_addc_u32 s25, s25, 0
	s_cmp_gt_u32 s65, 29
	s_cbranch_scc0 .LBB0_892
	s_and_b64 vcc, exec, s[10:11]
	s_cbranch_vccz .LBB0_895
	s_barrier

; __device__ __forceinline__ unsigned xb_ld(unsigned* p)              { return __hip_atomic_load(p, __ATOMIC_RELAXED, __HIP_MEMORY_SCOPE_AGENT); }
; __device__ __forceinline__ void xcd_barrier_complete(unsigned* bar, unsigned x, unsigned& nloc, unsigned& nx) {
;     const unsigned G = gridDim.x * gridDim.y * gridDim.z;
;     unsigned sum, cnt, mine, sp = 0u;
;     for (;;) {
;         sum = 0u; cnt = 0u; mine = 0u;
; #pragma unroll
;         for (unsigned j = 0; j < 16; ++j) { const unsigned c = xb_ld(&bar[XB_XCNT(j)]); sum += c; cnt += (c > 0u) ? 1u : 0u; mine = (j == x) ? c : mine; }
; __device__ __forceinline__ void xcd_barrier(const XcdBarrier& b) {
;     asm volatile("s_waitcnt vmcnt(0)" ::: "memory");
;     __syncthreads();
;     if (threadIdx.x == 0) {
;         unsigned* bar = b.bar;
;         __builtin_amdgcn_s_waitcnt(0);
;         unsigned nloc = b.st[0], nx = b.st[1];
;         if (nloc == 0u) { xcd_barrier_complete(bar, b.x, nloc, nx); b.st[0] = nloc; b.st[1] = nx; }
.LBB0_899:
	s_setprio 0
	s_cmp_gt_i32 s81, 8
	s_cselect_b64 s[0:1], -1, 0
	s_and_b64 s[2:3], s[2:3], s[0:1]
	s_andn2_b64 vcc, exec, s[2:3]
	s_cbranch_vccnz .LBB0_953
	s_waitcnt vmcnt(0)
	s_waitcnt vmcnt(0)
	s_barrier
	s_and_saveexec_b64 s[2:3], s[94:95]
	s_cbranch_execz .LBB0_952
	s_add_i32 s6, 0, 0x23fc0
	v_mov_b32_e32 v0, s6
	s_waitcnt vmcnt(0) expcnt(0) lgkmcnt(0)
	ds_read_b32 v2, v0
	s_add_i32 s6, 0, 0x23fc4
	v_mov_b32_e32 v0, s6
	ds_read_b32 v0, v0
	s_waitcnt lgkmcnt(1)
	v_cmp_ne_u32_e32 vcc, 0, v2
	s_cbranch_vccnz .LBB0_916
	v_readlane_b32 s6, v241, 0
	s_mul_i32 s33, s83, s6
	s_add_u32 s6, s90, 0x88200
	s_addc_u32 s7, s91, 0
	s_add_u32 s8, s90, 0x88400
	s_addc_u32 s9, s91, 0
	s_add_u32 s10, s90, 0x88500
	s_addc_u32 s11, s91, 0
	s_add_u32 s12, s90, 0x88600
	s_addc_u32 s13, s91, 0
	s_add_u32 s14, s90, 0x88700
	s_addc_u32 s15, s91, 0
	s_add_u32 s16, s90, 0x88800
	s_addc_u32 s17, s91, 0
	s_add_u32 s18, s90, 0x88900
	s_addc_u32 s19, s91, 0
	s_add_u32 s20, s90, 0x88a00
	s_addc_u32 s21, s91, 0
	s_add_u32 s22, s90, 0x88b00
	s_addc_u32 s23, s91, 0
	s_add_u32 s24, s90, 0x88c00
	s_addc_u32 s25, s91, 0
	s_add_u32 s26, s90, 0x88d00
	s_addc_u32 s27, s91, 0
	s_add_u32 s28, s90, 0x88e00
	s_addc_u32 s29, s91, 0
	s_add_u32 s30, s90, 0x88f00
	s_addc_u32 s31, s91, 0
	s_add_u32 s34, s90, 0x89000
	s_addc_u32 s35, s91, 0
	s_add_u32 s36, s90, 0x89100
	s_addc_u32 s37, s91, 0
	s_add_u32 s38, s90, 0x89200
	s_addc_u32 s39, s91, 0
	s_add_u32 s40, s90, 0x89300
	s_mul_i32 s33, s33, s82
	s_addc_u32 s41, s91, 0
	s_mov_b32 s48, 1
	v_mov_b32_e32 v16, 0
	s_branch .LBB0_904

;     __device__ __forceinline__ bool next(int i, Unit& u) const {
;         long L = (long)i * G + c; bool second = false;
;         if (L >= s0.count) { L -= s0.count; second = true; if (L >= s1.count) return false; }
;         const char* qa = second ? s1.a : s0.a; const char* qb = second ? s1.b : s0.b;
;         const int nM = second ? s1.nM : s0.nM, nN = second ? s1.nN : s0.nN, ks = second ? s1.ks : s0.ks, qnt = second ? s1.nt : s0.nt, mode = second ? s1.mode : s0.mode;
;         const int ksi = (int)(L % ks); int wgid = (int)(L / ks); const int nwg = nM * nN;
; __device__ __forceinline__ void run_gemm_store(const Params& p, LAS unsigned char* ldsl, const int ph) {
;     ...
;     else if (ph == 10) { E.ldc0 = NQK; S.add(A, ws + WS_WQKV, MALL / 256, NQK / 256, 1, D / 64, 0); S.add((const bf16_t*)(ws + WS_WQKV) + (size_t)NQK * D, A, D / 256, MALL / 256, 1, D / 64, 1); }
.LBB0_1121:
	s_cmp_lt_i32 s80, 11
	s_cselect_b64 s[2:3], -1, 0
	s_and_b64 s[0:1], s[2:3], s[0:1]
	s_andn2_b64 vcc, exec, s[0:1]
	s_cbranch_vccnz .LBB0_1142
	v_readfirstlane_b32 s101, v162
	s_nop 3
	s_lshr_b32 s101, s101, 6
	s_cmp_ge_u32 s101, 4
	s_cbranch_scc0 .Lsp_26088
	s_setprio 1
.Lsp_26088:
	s_ashr_i32 s30, s92, 31
	s_cmpk_lt_i32 s92, 0x440
	s_cselect_b64 s[8:9], -1, 0
	v_readfirstlane_b32 s10, v162
	s_and_b64 vcc, exec, s[8:9]
	s_cbranch_vccnz .LBB0_1124
	s_add_u32 s2, s92, 0xfffffbc0
	s_addc_u32 s3, s30, -1
	v_mov_b64_e32 v[0:1], 0x220
	v_cmp_lt_u64_e64 s[8:9], s[2:3], v[0:1]
	s_mov_b32 s38, 1
	s_movk_i32 s14, 0x44
	s_mov_b32 s13, 8
	s_mov_b64 s[6:7], 0xc600000
	s_mov_b64 s[4:5], 0xae00000
	s_andn2_b64 vcc, exec, s[8:9]
	s_cbranch_vccz .LBB0_1125
	s_branch .LBB0_1142

; #define PG8_STAGE(bufoff, gbase, voff) do { _Pragma("unroll") for (int _i = 0; _i < 2; ++_i) \
;         __builtin_amdgcn_global_load_lds((const unsigned*)((const char*)(gbase) + (voff)[_i]), (LAS unsigned*)(lds + (bufoff) + ldsw + _i * 8192), 16, 0, 0); } while (0)
; #define PG8_LDA(dst, b, h) do { _Pragma("unroll") for (int m = 0; m < 4; ++m) _Pragma("unroll") for (int k = 0; k < 2; ++k) dst[m][k] = *(const LAS bf16x8*)(lds + PG8_SA(b, h) + aoff + m * 2048 + k * 1024); } while (0)
; #define PG8_LDB(dst, b, h) do { _Pragma("unroll") for (int n = 0; n < 2; ++n) _Pragma("unroll") for (int k = 0; k < 2; ++k) dst[n][k] = *(const LAS bf16x8*)(lds + PG8_SB(b, h) + boff + n * 2048 + k * 1024); } while (0)
; #define PG8_MMA(ai, bj, At, Bt) do { __builtin_amdgcn_s_setprio(1); _Pragma("unroll") for (int m = 0; m < 4; ++m) _Pragma("unroll") for (int n = 0; n < 2; ++n) _Pragma("unroll") for (int k = 0; k < 2; ++k) \
;         acc[ai][bj][m][n] = __builtin_amdgcn_mfma_f32_16x16x32_bf16(Bt[n][k], At[m][k], acc[ai][bj][m][n], 0, 0, 0); __builtin_amdgcn_s_setprio(0); } while (0)
; #define PG8_WAIT_V(n) asm volatile("s_waitcnt vmcnt(" #n ")" ::: "memory")
; #define PG8_WAIT_L(n) asm volatile("s_waitcnt lgkmcnt(" #n ")" ::: "memory")
; #define PG8_BAR __builtin_amdgcn_s_barrier()
; template <class Epi, class Sched, bool ALIGN_EPI = false, bool SP2 = false>
; __device__ __forceinline__ void gemm_phase(LAS unsigned char* lds, const Gemm g, const Sched& S, const Epi& E) {
;     ...
;             const bool last = (t == nt - 2);
;             const char* a1 = cA + (size_t)(t + 1) * kstep;
;             const char* a2 = last ? nA : cA + (size_t)(t + 2) * kstep; const char* b2 = last ? nB : cB + (size_t)(t + 2) * kstep;
;             const char* a3 = a2 + kstep; const char* b3 = b2 + kstep;
;             if (last && has_next) S.a_ready(nxt);
;             if constexpr (SP2) {
;             PG8_LDB(B0, 0, 0); PG8_LDB(B1, 0, 1); PG8_SCHED; PG8_LDA(At, 0, 0); PG8_STAGE(PG8_SA(1, 1), a1 + hstep, voffA);
;             PG8_WAIT_V(8); PG8_WAIT_L(0); PG8_BAR; PG8_MMA(0, 0, At, B0); PG8_MMA(0, 1, At, B1); PG8_BAR; PG8_SCHED;
;             PG8_LDA(At, 0, 1); PG8_STAGE(PG8_SB(0, 0), b2, voffB); PG8_STAGE(PG8_SB(0, 1), b2 + hstep, voffB); PG8_STAGE(PG8_SA(0, 0), a2, voffA);
;             PG8_WAIT_V(8); PG8_WAIT_L(0); PG8_BAR; PG8_MMA(1, 0, At, B0); PG8_MMA(1, 1, At, B1); PG8_BAR; PG8_SCHED;
.LBB0_1135:
	ds_read_b128 v[150:153], v147
	ds_read_b128 v[154:157], v147 offset:1024
	ds_read_b128 v[164:167], v147 offset:2048
	ds_read_b128 v[170:173], v147 offset:3072
	ds_read_b128 v[174:177], v148
	ds_read_b128 v[178:181], v148 offset:1024
	ds_read_b128 v[182:185], v148 offset:2048
	ds_read_b128 v[186:189], v148 offset:3072
	s_add_u32 s22, s20, 0xfff80080
	s_addc_u32 s23, s21, -1
	s_cmp_eq_u32 s48, 28
	s_cselect_b32 s25, s13, s23
	s_cselect_b32 s24, s26, s22
	s_cselect_b32 s23, s27, s47
	s_cselect_b32 s22, s28, s29
	v_lshl_add_u64 v[158:159], s[20:21], 0, v[136:137]
	s_add_i32 m0, s33, 0xc000
	ds_read_b128 v[190:193], v149
	ds_read_b128 v[194:197], v149 offset:1024
	ds_read_b128 v[198:201], v149 offset:2048
	ds_read_b128 v[202:205], v149 offset:3072
	ds_read_b128 v[206:209], v149 offset:4096
	ds_read_b128 v[210:213], v149 offset:5120
	ds_read_b128 v[214:217], v149 offset:6144
	ds_read_b128 v[218:221], v149 offset:7168
	global_load_lds_dwordx4 v[158:159], off
	v_lshl_add_u64 v[158:159], s[20:21], 0, v[138:139]
	s_add_i32 m0, s33, 0xe000
	s_nop 0
	global_load_lds_dwordx4 v[158:159], off
	s_waitcnt vmcnt(8)
	s_waitcnt lgkmcnt(0)
	s_barrier
	s_waitcnt lgkmcnt(0)
	v_mfma_f32_16x16x32_bf16 v[124:127], v[150:153], v[190:193], v[124:127]
	v_mfma_f32_16x16x32_bf16 v[120:123], v[164:167], v[190:193], v[120:123]
	v_mfma_f32_16x16x32_bf16 v[116:119], v[150:153], v[198:201], v[116:119]
	v_mfma_f32_16x16x32_bf16 v[112:115], v[164:167], v[198:201], v[112:115]
	v_mfma_f32_16x16x32_bf16 v[100:103], v[150:153], v[206:209], v[100:103]
	v_mfma_f32_16x16x32_bf16 v[96:99], v[164:167], v[206:209], v[96:99]
	v_mfma_f32_16x16x32_bf16 v[84:87], v[150:153], v[214:217], v[84:87]
	v_mfma_f32_16x16x32_bf16 v[80:83], v[164:167], v[214:217], v[80:83]
	v_mfma_f32_16x16x32_bf16 v[124:127], v[154:157], v[194:197], v[124:127]
	v_mfma_f32_16x16x32_bf16 v[120:123], v[170:173], v[194:197], v[120:123]
	v_mfma_f32_16x16x32_bf16 v[116:119], v[154:157], v[202:205], v[116:119]
	v_mfma_f32_16x16x32_bf16 v[112:115], v[170:173], v[202:205], v[112:115]
	v_mfma_f32_16x16x32_bf16 v[100:103], v[154:157], v[210:213], v[100:103]
	v_mfma_f32_16x16x32_bf16 v[96:99], v[170:173], v[210:213], v[96:99]
	v_mfma_f32_16x16x32_bf16 v[84:87], v[154:157], v[218:221], v[84:87]
	v_mfma_f32_16x16x32_bf16 v[80:83], v[170:173], v[218:221], v[80:83]
	v_mfma_f32_16x16x32_bf16 v[108:111], v[174:177], v[190:193], v[108:111]
	v_mfma_f32_16x16x32_bf16 v[104:107], v[182:185], v[190:193], v[104:107]
	v_mfma_f32_16x16x32_bf16 v[92:95], v[174:177], v[198:201], v[92:95]
	v_mfma_f32_16x16x32_bf16 v[88:91], v[182:185], v[198:201], v[88:91]
	v_mfma_f32_16x16x32_bf16 v[76:79], v[174:177], v[206:209], v[76:79]
	v_mfma_f32_16x16x32_bf16 v[72:75], v[182:185], v[206:209], v[72:75]
	v_mfma_f32_16x16x32_bf16 v[68:71], v[174:177], v[214:217], v[68:71]
	v_mfma_f32_16x16x32_bf16 v[64:67], v[182:185], v[214:217], v[64:67]
	v_mfma_f32_16x16x32_bf16 v[108:111], v[178:181], v[194:197], v[108:111]
	v_mfma_f32_16x16x32_bf16 v[104:107], v[186:189], v[194:197], v[104:107]
	v_mfma_f32_16x16x32_bf16 v[92:95], v[178:181], v[202:205], v[92:95]
	v_mfma_f32_16x16x32_bf16 v[88:91], v[186:189], v[202:205], v[88:91]
	v_mfma_f32_16x16x32_bf16 v[76:79], v[178:181], v[210:213], v[76:79]
	v_mfma_f32_16x16x32_bf16 v[72:75], v[186:189], v[210:213], v[72:75]
	v_mfma_f32_16x16x32_bf16 v[68:71], v[178:181], v[218:221], v[68:71]
	v_mfma_f32_16x16x32_bf16 v[64:67], v[186:189], v[218:221], v[64:67]
	s_barrier
	s_add_i32 s49, s43, s31
	v_lshl_add_u64 v[158:159], s[22:23], 0, v[130:131]
	s_mov_b32 m0, s49
	ds_read_b128 v[190:193], v149 offset:16384
	ds_read_b128 v[194:197], v149 offset:17408
	ds_read_b128 v[198:201], v149 offset:18432
	ds_read_b128 v[202:205], v149 offset:19456
	ds_read_b128 v[206:209], v149 offset:20480
	ds_read_b128 v[210:213], v149 offset:21504
	ds_read_b128 v[214:217], v149 offset:22528
	ds_read_b128 v[218:221], v149 offset:23552
	global_load_lds_dwordx4 v[158:159], off
	s_add_i32 m0, s49, 0x2000
	s_add_u32 s50, s22, 0x80000
	v_lshl_add_u64 v[222:223], s[22:23], 0, v[134:135]
	s_addc_u32 s51, s23, 0
	s_add_i32 s49, s44, s31
	global_load_lds_dwordx4 v[222:223], off
	v_lshl_add_u64 v[224:225], s[50:51], 0, v[130:131]
	s_mov_b32 m0, s49
	v_lshl_add_u64 v[226:227], s[24:25], 0, v[132:133]
	global_load_lds_dwordx4 v[224:225], off
	v_lshl_add_u64 v[224:225], s[50:51], 0, v[134:135]
	s_add_i32 m0, s49, 0x2000
	s_nop 0
	global_load_lds_dwordx4 v[224:225], off
	v_lshl_add_u64 v[224:225], s[24:25], 0, v[128:129]
	s_mov_b32 m0, s33
	s_nop 0
	global_load_lds_dwordx4 v[224:225], off
	s_mov_b32 m0, s34
	s_nop 0
	global_load_lds_dwordx4 v[226:227], off
	s_waitcnt vmcnt(8)
	s_waitcnt lgkmcnt(0)
	s_barrier
; #define PG8_STAGE(bufoff, gbase, voff) do { _Pragma("unroll") for (int _i = 0; _i < 2; ++_i) \
;         __builtin_amdgcn_global_load_lds((const unsigned*)((const char*)(gbase) + (voff)[_i]), (LAS unsigned*)(lds + (bufoff) + ldsw + _i * 8192), 16, 0, 0); } while (0)
; #define PG8_LDA(dst, b, h) do { _Pragma("unroll") for (int m = 0; m < 4; ++m) _Pragma("unroll") for (int k = 0; k < 2; ++k) dst[m][k] = *(const LAS bf16x8*)(lds + PG8_SA(b, h) + aoff + m * 2048 + k * 1024); } while (0)
; #define PG8_LDB(dst, b, h) do { _Pragma("unroll") for (int n = 0; n < 2; ++n) _Pragma("unroll") for (int k = 0; k < 2; ++k) dst[n][k] = *(const LAS bf16x8*)(lds + PG8_SB(b, h) + boff + n * 2048 + k * 1024); } while (0)
; #define PG8_MMA(ai, bj, At, Bt) do { __builtin_amdgcn_s_setprio(1); _Pragma("unroll") for (int m = 0; m < 4; ++m) _Pragma("unroll") for (int n = 0; n < 2; ++n) _Pragma("unroll") for (int k = 0; k < 2; ++k) \
;         acc[ai][bj][m][n] = __builtin_amdgcn_mfma_f32_16x16x32_bf16(Bt[n][k], At[m][k], acc[ai][bj][m][n], 0, 0, 0); __builtin_amdgcn_s_setprio(0); } while (0)
; #define PG8_WAIT_V(n) asm volatile("s_waitcnt vmcnt(" #n ")" ::: "memory")
; #define PG8_WAIT_L(n) asm volatile("s_waitcnt lgkmcnt(" #n ")" ::: "memory")
; #define PG8_BAR __builtin_amdgcn_s_barrier()
; #define PG8_SCHED __builtin_amdgcn_sched_barrier(0)
; template <class Epi, class Sched, bool ALIGN_EPI = false, bool SP2 = false>
; __device__ __forceinline__ void gemm_phase(LAS unsigned char* lds, const Gemm g, const Sched& S, const Epi& E) {
;     ...
;             PG8_WAIT_V(8); PG8_WAIT_L(0); PG8_BAR; PG8_MMA(1, 0, At, B0); PG8_MMA(1, 1, At, B1); PG8_BAR; PG8_SCHED;
;             PG8_LDB(B0, 1, 0); PG8_LDB(B1, 1, 1); PG8_SCHED; PG8_LDA(At, 1, 0); PG8_STAGE(PG8_SA(0, 1), a2 + hstep, voffA);
;             PG8_WAIT_V(8); PG8_WAIT_L(0); PG8_BAR; PG8_MMA(0, 0, At, B0); PG8_MMA(0, 1, At, B1); PG8_BAR; PG8_SCHED;
	s_waitcnt lgkmcnt(0)
	v_mfma_f32_16x16x32_bf16 v[60:63], v[150:153], v[190:193], v[60:63]
	v_mfma_f32_16x16x32_bf16 v[56:59], v[164:167], v[190:193], v[56:59]
	v_mfma_f32_16x16x32_bf16 v[52:55], v[150:153], v[198:201], v[52:55]
	v_mfma_f32_16x16x32_bf16 v[48:51], v[164:167], v[198:201], v[48:51]
	v_mfma_f32_16x16x32_bf16 v[36:39], v[150:153], v[206:209], v[36:39]
	v_mfma_f32_16x16x32_bf16 v[32:35], v[164:167], v[206:209], v[32:35]
	v_mfma_f32_16x16x32_bf16 v[20:23], v[150:153], v[214:217], v[20:23]
	v_mfma_f32_16x16x32_bf16 v[16:19], v[164:167], v[214:217], v[16:19]
	v_mfma_f32_16x16x32_bf16 v[60:63], v[154:157], v[194:197], v[60:63]
	v_mfma_f32_16x16x32_bf16 v[56:59], v[170:173], v[194:197], v[56:59]
	v_mfma_f32_16x16x32_bf16 v[52:55], v[154:157], v[202:205], v[52:55]
	v_mfma_f32_16x16x32_bf16 v[48:51], v[170:173], v[202:205], v[48:51]
	v_mfma_f32_16x16x32_bf16 v[36:39], v[154:157], v[210:213], v[36:39]
	v_mfma_f32_16x16x32_bf16 v[32:35], v[170:173], v[210:213], v[32:35]
	v_mfma_f32_16x16x32_bf16 v[20:23], v[154:157], v[218:221], v[20:23]
	v_mfma_f32_16x16x32_bf16 v[16:19], v[170:173], v[218:221], v[16:19]
	v_mfma_f32_16x16x32_bf16 v[44:47], v[174:177], v[190:193], v[44:47]
	v_mfma_f32_16x16x32_bf16 v[40:43], v[182:185], v[190:193], v[40:43]
	v_mfma_f32_16x16x32_bf16 v[28:31], v[174:177], v[198:201], v[28:31]
	v_mfma_f32_16x16x32_bf16 v[24:27], v[182:185], v[198:201], v[24:27]
	v_mfma_f32_16x16x32_bf16 v[12:15], v[174:177], v[206:209], v[12:15]
	v_mfma_f32_16x16x32_bf16 v[8:11], v[182:185], v[206:209], v[8:11]
	v_mfma_f32_16x16x32_bf16 v[4:7], v[174:177], v[214:217], v[4:7]
	v_mfma_f32_16x16x32_bf16 v[0:3], v[182:185], v[214:217], v[0:3]
	v_mfma_f32_16x16x32_bf16 v[44:47], v[178:181], v[194:197], v[44:47]
	v_mfma_f32_16x16x32_bf16 v[40:43], v[186:189], v[194:197], v[40:43]
	v_mfma_f32_16x16x32_bf16 v[28:31], v[178:181], v[202:205], v[28:31]
	v_mfma_f32_16x16x32_bf16 v[24:27], v[186:189], v[202:205], v[24:27]
	v_mfma_f32_16x16x32_bf16 v[12:15], v[178:181], v[210:213], v[12:15]
	v_mfma_f32_16x16x32_bf16 v[8:11], v[186:189], v[210:213], v[8:11]
	v_mfma_f32_16x16x32_bf16 v[4:7], v[178:181], v[218:221], v[4:7]
	v_mfma_f32_16x16x32_bf16 v[0:3], v[186:189], v[218:221], v[0:3]
	s_barrier
	s_add_i32 s49, 0, 0x18000
	v_add_u32_e32 v163, s49, v145
	s_add_i32 s50, 0, 0x1c000
	ds_read_b128 v[150:153], v163
	ds_read_b128 v[154:157], v163 offset:1024
	ds_read_b128 v[164:167], v163 offset:2048
	ds_read_b128 v[170:173], v163 offset:3072
	v_add_u32_e32 v163, s50, v145
	ds_read_b128 v[174:177], v163
	ds_read_b128 v[178:181], v163 offset:1024
	ds_read_b128 v[182:185], v163 offset:2048
	ds_read_b128 v[186:189], v163 offset:3072
	s_add_u32 s24, s24, 0x80000
	s_addc_u32 s25, s25, 0
	s_mov_b32 m0, s35
	v_lshl_add_u64 v[228:229], s[24:25], 0, v[128:129]
	ds_read_b128 v[190:193], v149 offset:32768
	ds_read_b128 v[194:197], v149 offset:33792
	ds_read_b128 v[198:201], v149 offset:34816
	ds_read_b128 v[202:205], v149 offset:35840
	ds_read_b128 v[206:209], v149 offset:36864
	ds_read_b128 v[210:213], v149 offset:37888
	ds_read_b128 v[214:217], v149 offset:38912
	ds_read_b128 v[218:221], v149 offset:39936
	global_load_lds_dwordx4 v[228:229], off
	v_lshl_add_u64 v[228:229], s[24:25], 0, v[132:133]
	s_mov_b32 m0, s36
	s_nop 0
	global_load_lds_dwordx4 v[228:229], off
	s_waitcnt vmcnt(8)
	s_waitcnt lgkmcnt(0)
	s_barrier
	s_waitcnt lgkmcnt(0)
	v_mfma_f32_16x16x32_bf16 v[124:127], v[150:153], v[190:193], v[124:127]
	v_mfma_f32_16x16x32_bf16 v[120:123], v[164:167], v[190:193], v[120:123]
	v_mfma_f32_16x16x32_bf16 v[116:119], v[150:153], v[198:201], v[116:119]
	v_mfma_f32_16x16x32_bf16 v[112:115], v[164:167], v[198:201], v[112:115]
	v_mfma_f32_16x16x32_bf16 v[100:103], v[150:153], v[206:209], v[100:103]
	v_mfma_f32_16x16x32_bf16 v[96:99], v[164:167], v[206:209], v[96:99]
	v_mfma_f32_16x16x32_bf16 v[84:87], v[150:153], v[214:217], v[84:87]
	v_mfma_f32_16x16x32_bf16 v[80:83], v[164:167], v[214:217], v[80:83]
	v_mfma_f32_16x16x32_bf16 v[124:127], v[154:157], v[194:197], v[124:127]
	v_mfma_f32_16x16x32_bf16 v[120:123], v[170:173], v[194:197], v[120:123]
	v_mfma_f32_16x16x32_bf16 v[116:119], v[154:157], v[202:205], v[116:119]
	v_mfma_f32_16x16x32_bf16 v[112:115], v[170:173], v[202:205], v[112:115]
	v_mfma_f32_16x16x32_bf16 v[100:103], v[154:157], v[210:213], v[100:103]
	v_mfma_f32_16x16x32_bf16 v[96:99], v[170:173], v[210:213], v[96:99]
	v_mfma_f32_16x16x32_bf16 v[84:87], v[154:157], v[218:221], v[84:87]
	v_mfma_f32_16x16x32_bf16 v[80:83], v[170:173], v[218:221], v[80:83]
	v_mfma_f32_16x16x32_bf16 v[108:111], v[174:177], v[190:193], v[108:111]
	v_mfma_f32_16x16x32_bf16 v[104:107], v[182:185], v[190:193], v[104:107]
	v_mfma_f32_16x16x32_bf16 v[92:95], v[174:177], v[198:201], v[92:95]
	v_mfma_f32_16x16x32_bf16 v[88:91], v[182:185], v[198:201], v[88:91]
	v_mfma_f32_16x16x32_bf16 v[76:79], v[174:177], v[206:209], v[76:79]
	v_mfma_f32_16x16x32_bf16 v[72:75], v[182:185], v[206:209], v[72:75]
	v_mfma_f32_16x16x32_bf16 v[68:71], v[174:177], v[214:217], v[68:71]
	v_mfma_f32_16x16x32_bf16 v[64:67], v[182:185], v[214:217], v[64:67]
	v_mfma_f32_16x16x32_bf16 v[108:111], v[178:181], v[194:197], v[108:111]
	v_mfma_f32_16x16x32_bf16 v[104:107], v[186:189], v[194:197], v[104:107]
	v_mfma_f32_16x16x32_bf16 v[92:95], v[178:181], v[202:205], v[92:95]
	v_mfma_f32_16x16x32_bf16 v[88:91], v[186:189], v[202:205], v[88:91]
	v_mfma_f32_16x16x32_bf16 v[76:79], v[178:181], v[210:213], v[76:79]
	v_mfma_f32_16x16x32_bf16 v[72:75], v[186:189], v[210:213], v[72:75]
	v_mfma_f32_16x16x32_bf16 v[68:71], v[178:181], v[218:221], v[68:71]
	v_mfma_f32_16x16x32_bf16 v[64:67], v[186:189], v[218:221], v[64:67]
	s_barrier
; #define PG8_STAGE(bufoff, gbase, voff) do { _Pragma("unroll") for (int _i = 0; _i < 2; ++_i) \
;         __builtin_amdgcn_global_load_lds((const unsigned*)((const char*)(gbase) + (voff)[_i]), (LAS unsigned*)(lds + (bufoff) + ldsw + _i * 8192), 16, 0, 0); } while (0)
; #define PG8_LDA(dst, b, h) do { _Pragma("unroll") for (int m = 0; m < 4; ++m) _Pragma("unroll") for (int k = 0; k < 2; ++k) dst[m][k] = *(const LAS bf16x8*)(lds + PG8_SA(b, h) + aoff + m * 2048 + k * 1024); } while (0)
; #define PG8_MMA(ai, bj, At, Bt) do { __builtin_amdgcn_s_setprio(1); _Pragma("unroll") for (int m = 0; m < 4; ++m) _Pragma("unroll") for (int n = 0; n < 2; ++n) _Pragma("unroll") for (int k = 0; k < 2; ++k) \
;         acc[ai][bj][m][n] = __builtin_amdgcn_mfma_f32_16x16x32_bf16(Bt[n][k], At[m][k], acc[ai][bj][m][n], 0, 0, 0); __builtin_amdgcn_s_setprio(0); } while (0)
; #define PG8_WAIT_V(n) asm volatile("s_waitcnt vmcnt(" #n ")" ::: "memory")
; #define PG8_WAIT_L(n) asm volatile("s_waitcnt lgkmcnt(" #n ")" ::: "memory")
; #define PG8_BAR __builtin_amdgcn_s_barrier()
; #define PG8_SCHED __builtin_amdgcn_sched_barrier(0)
; template <class Epi, class Sched, bool ALIGN_EPI = false, bool SP2 = false>
; __device__ __forceinline__ void gemm_phase(LAS unsigned char* lds, const Gemm g, const Sched& S, const Epi& E) {
;     ...
;             PG8_LDA(At, 1, 1); PG8_STAGE(PG8_SB(1, 0), b3, voffB); PG8_STAGE(PG8_SB(1, 1), b3 + hstep, voffB); PG8_STAGE(PG8_SA(1, 0), a3, voffA);
;             PG8_WAIT_V(8); PG8_WAIT_L(0); PG8_BAR; PG8_MMA(1, 0, At, B0); PG8_MMA(1, 1, At, B1); PG8_BAR; PG8_SCHED;
	s_add_i32 s24, s49, s31
	v_lshl_add_u64 v[158:159], v[158:159], 0, s[4:5]
	s_mov_b32 m0, s24
	ds_read_b128 v[190:193], v149 offset:49152
	ds_read_b128 v[194:197], v149 offset:50176
	ds_read_b128 v[198:201], v149 offset:51200
	ds_read_b128 v[202:205], v149 offset:52224
	ds_read_b128 v[206:209], v149 offset:53248
	ds_read_b128 v[210:213], v149 offset:54272
	ds_read_b128 v[214:217], v149 offset:55296
	ds_read_b128 v[218:221], v149 offset:56320
	global_load_lds_dwordx4 v[158:159], off
	s_add_i32 m0, s24, 0x2000
	s_add_u32 s22, s22, 0x80080
	v_lshl_add_u64 v[158:159], v[222:223], 0, s[4:5]
	s_addc_u32 s23, s23, 0
	s_add_i32 s24, s50, s31
	global_load_lds_dwordx4 v[158:159], off
	v_lshl_add_u64 v[158:159], s[22:23], 0, v[130:131]
	s_mov_b32 m0, s24
	s_nop 0
	global_load_lds_dwordx4 v[158:159], off
	v_lshl_add_u64 v[158:159], s[22:23], 0, v[134:135]
	s_add_i32 m0, s24, 0x2000
	s_nop 0
	global_load_lds_dwordx4 v[158:159], off
	v_lshl_add_u64 v[158:159], v[224:225], 0, s[4:5]
	s_mov_b32 m0, s40
	s_nop 0
	global_load_lds_dwordx4 v[158:159], off
	v_lshl_add_u64 v[158:159], v[226:227], 0, s[4:5]
	s_mov_b32 m0, s41
	s_nop 0
	global_load_lds_dwordx4 v[158:159], off
	s_waitcnt vmcnt(8)
	s_waitcnt lgkmcnt(0)
	s_barrier
	s_waitcnt lgkmcnt(0)
	v_mfma_f32_16x16x32_bf16 v[60:63], v[150:153], v[190:193], v[60:63]
	v_mfma_f32_16x16x32_bf16 v[56:59], v[164:167], v[190:193], v[56:59]
	v_mfma_f32_16x16x32_bf16 v[52:55], v[150:153], v[198:201], v[52:55]
	v_mfma_f32_16x16x32_bf16 v[48:51], v[164:167], v[198:201], v[48:51]
	v_mfma_f32_16x16x32_bf16 v[36:39], v[150:153], v[206:209], v[36:39]
	v_mfma_f32_16x16x32_bf16 v[32:35], v[164:167], v[206:209], v[32:35]
	v_mfma_f32_16x16x32_bf16 v[20:23], v[150:153], v[214:217], v[20:23]
	v_mfma_f32_16x16x32_bf16 v[16:19], v[164:167], v[214:217], v[16:19]
	v_mfma_f32_16x16x32_bf16 v[60:63], v[154:157], v[194:197], v[60:63]
	v_mfma_f32_16x16x32_bf16 v[56:59], v[170:173], v[194:197], v[56:59]
	v_mfma_f32_16x16x32_bf16 v[52:55], v[154:157], v[202:205], v[52:55]
	v_mfma_f32_16x16x32_bf16 v[48:51], v[170:173], v[202:205], v[48:51]
	v_mfma_f32_16x16x32_bf16 v[36:39], v[154:157], v[210:213], v[36:39]
	v_mfma_f32_16x16x32_bf16 v[32:35], v[170:173], v[210:213], v[32:35]
	v_mfma_f32_16x16x32_bf16 v[20:23], v[154:157], v[218:221], v[20:23]
	v_mfma_f32_16x16x32_bf16 v[16:19], v[170:173], v[218:221], v[16:19]
	v_mfma_f32_16x16x32_bf16 v[44:47], v[174:177], v[190:193], v[44:47]
	v_mfma_f32_16x16x32_bf16 v[40:43], v[182:185], v[190:193], v[40:43]
	v_mfma_f32_16x16x32_bf16 v[28:31], v[174:177], v[198:201], v[28:31]
	v_mfma_f32_16x16x32_bf16 v[24:27], v[182:185], v[198:201], v[24:27]
	v_mfma_f32_16x16x32_bf16 v[12:15], v[174:177], v[206:209], v[12:15]
	v_mfma_f32_16x16x32_bf16 v[8:11], v[182:185], v[206:209], v[8:11]
	v_mfma_f32_16x16x32_bf16 v[4:7], v[174:177], v[214:217], v[4:7]
	v_mfma_f32_16x16x32_bf16 v[0:3], v[182:185], v[214:217], v[0:3]
	v_mfma_f32_16x16x32_bf16 v[44:47], v[178:181], v[194:197], v[44:47]
	v_mfma_f32_16x16x32_bf16 v[40:43], v[186:189], v[194:197], v[40:43]
	v_mfma_f32_16x16x32_bf16 v[28:31], v[178:181], v[202:205], v[28:31]
	v_mfma_f32_16x16x32_bf16 v[24:27], v[186:189], v[202:205], v[24:27]
	v_mfma_f32_16x16x32_bf16 v[12:15], v[178:181], v[210:213], v[12:15]
	v_mfma_f32_16x16x32_bf16 v[8:11], v[186:189], v[210:213], v[8:11]
	v_mfma_f32_16x16x32_bf16 v[4:7], v[178:181], v[218:221], v[4:7]
	v_mfma_f32_16x16x32_bf16 v[0:3], v[186:189], v[218:221], v[0:3]
	s_barrier
	s_add_i32 s48, s48, 2
	s_add_u32 s20, s20, 0x100
	s_addc_u32 s21, s21, 0
	s_add_u32 s29, s29, 0x100
	s_addc_u32 s47, s47, 0
	s_cmp_gt_u32 s48, 29
	s_cbranch_scc0 .LBB0_1135
	s_and_b64 vcc, exec, s[6:7]
	s_cbranch_vccz .LBB0_1138
	s_barrier

; __device__ __forceinline__ unsigned xb_ld(unsigned* p)              { return __hip_atomic_load(p, __ATOMIC_RELAXED, __HIP_MEMORY_SCOPE_AGENT); }
; __device__ __forceinline__ void xcd_barrier_complete(unsigned* bar, unsigned x, unsigned& nloc, unsigned& nx) {
;     const unsigned G = gridDim.x * gridDim.y * gridDim.z;
;     unsigned sum, cnt, mine, sp = 0u;
;     for (;;) {
;         sum = 0u; cnt = 0u; mine = 0u;
; #pragma unroll
;         for (unsigned j = 0; j < 16; ++j) { const unsigned c = xb_ld(&bar[XB_XCNT(j)]); sum += c; cnt += (c > 0u) ? 1u : 0u; mine = (j == x) ? c : mine; }
; __device__ __forceinline__ void xcd_barrier(const XcdBarrier& b) {
;     asm volatile("s_waitcnt vmcnt(0)" ::: "memory");
;     __syncthreads();
;     if (threadIdx.x == 0) {
;         unsigned* bar = b.bar;
;         __builtin_amdgcn_s_waitcnt(0);
;         unsigned nloc = b.st[0], nx = b.st[1];
;         if (nloc == 0u) { xcd_barrier_complete(bar, b.x, nloc, nx); b.st[0] = nloc; b.st[1] = nx; }
.LBB0_1142:
	s_setprio 0
	s_cmp_gt_i32 s81, 11
	s_cselect_b64 s[2:3], -1, 0
	s_and_b64 s[0:1], s[0:1], s[2:3]
	s_andn2_b64 vcc, exec, s[0:1]
	s_cbranch_vccnz .LBB0_1196
	s_waitcnt vmcnt(0)
	s_waitcnt vmcnt(0)
	s_barrier
	s_and_saveexec_b64 s[0:1], s[94:95]
	s_cbranch_execz .LBB0_1195
	s_add_i32 s4, 0, 0x23fc0
	v_mov_b32_e32 v0, s4
	s_waitcnt vmcnt(0) expcnt(0) lgkmcnt(0)
	ds_read_b32 v2, v0
	s_add_i32 s4, 0, 0x23fc4
	v_mov_b32_e32 v0, s4
	ds_read_b32 v0, v0
	s_waitcnt lgkmcnt(1)
	v_cmp_ne_u32_e32 vcc, 0, v2
	s_cbranch_vccnz .LBB0_1159
	v_readlane_b32 s4, v241, 0
	s_mul_i32 s33, s83, s4
	s_add_u32 s4, s90, 0x88200
	s_addc_u32 s5, s91, 0
	s_add_u32 s6, s90, 0x88400
	s_addc_u32 s7, s91, 0
	s_add_u32 s8, s90, 0x88500
	s_addc_u32 s9, s91, 0
	s_add_u32 s10, s90, 0x88600
	s_addc_u32 s11, s91, 0
	s_add_u32 s12, s90, 0x88700
	s_addc_u32 s13, s91, 0
	s_add_u32 s14, s90, 0x88800
	s_addc_u32 s15, s91, 0
	s_add_u32 s16, s90, 0x88900
	s_addc_u32 s17, s91, 0
	s_add_u32 s18, s90, 0x88a00
	s_addc_u32 s19, s91, 0
	s_add_u32 s20, s90, 0x88b00
	s_addc_u32 s21, s91, 0
	s_add_u32 s22, s90, 0x88c00
	s_addc_u32 s23, s91, 0
	s_add_u32 s24, s90, 0x88d00
	s_addc_u32 s25, s91, 0
	s_add_u32 s26, s90, 0x88e00
	s_addc_u32 s27, s91, 0
	s_add_u32 s28, s90, 0x88f00
	s_addc_u32 s29, s91, 0
	s_add_u32 s30, s90, 0x89000
	s_addc_u32 s31, s91, 0
	s_add_u32 s34, s90, 0x89100
	s_addc_u32 s35, s91, 0
	s_add_u32 s36, s90, 0x89200
	s_addc_u32 s37, s91, 0
	s_add_u32 s38, s90, 0x89300
	s_mul_i32 s33, s33, s82
	s_addc_u32 s39, s91, 0
	s_mov_b32 s46, 1
	v_mov_b32_e32 v16, 0
	s_branch .LBB0_1147

;     __device__ __forceinline__ bool next(int i, Unit& u) const {
;         long L = (long)i * G + c; bool second = false;
;         if (L >= s0.count) { L -= s0.count; second = true; if (L >= s1.count) return false; }
;         const char* qa = second ? s1.a : s0.a; const char* qb = second ? s1.b : s0.b;
;         const int nM = second ? s1.nM : s0.nM, nN = second ? s1.nN : s0.nN, ks = second ? s1.ks : s0.ks, qnt = second ? s1.nt : s0.nt, mode = second ? s1.mode : s0.mode;
;         const int ksi = (int)(L % ks); int wgid = (int)(L / ks); const int nwg = nM * nN;
;         { const int qq = nwg / NXCD, r = nwg % NXCD, xcd = wgid % NXCD, off = wgid / NXCD; wgid = (xcd < r ? xcd * (qq + 1) : r * (qq + 1) + (xcd - r) * qq) + off; }
;         const int nig = WGM * nN, gid = wgid / nig, fm = gid * WGM, gsz = (nM - fm) < WGM ? (nM - fm) : WGM;
;         u.pm = fm + ((wgid % nig) % gsz); u.pn = (wgid % nig) / gsz; u.nt = qnt; u.mode = mode; u.ksi = ksi;
;         const size_t koff = (size_t)ksi * qnt * (BK * 2);
;         u.a = qa + (size_t)u.pm * tstep + koff; u.b = qb + (size_t)u.pn * tstep + koff; return true;
; template <class Epi, class Sched, bool ALIGN_EPI = false, bool SP2 = false>
; __device__ __forceinline__ void gemm_phase(LAS unsigned char* lds, const Gemm g, const Sched& S, const Epi& E) {
;     const int tid = threadIdx.x, wid = __builtin_amdgcn_readfirstlane(tid >> 6), lane = tid & 63, wr = wid >> 2, wc = wid & 3, fr = lane & 15, fq = lane >> 4;
;     const int K = g.ld;
;     unsigned voffA[2], voffB[2];
; #pragma unroll
;     for (int i = 0; i < 2; ++i) { int R, C; stage_rc(tid * 16 + i * 8192, R, C); const int Rb = Epi::PERM ? ((R & ~31) + perm32(R & 31)) : R;
;         voffA[i] = (unsigned)(R * K + C) * 2u; voffB[i] = (unsigned)(Rb * K + C) * 2u; }
;     const size_t kstep = (size_t)(BK * 2);
;     const size_t hstep = (size_t)HALF * K * 2;
;     const unsigned ldsw = (unsigned)wid * 1024u;
;     const int aoff = lds_byte(wr * 64 + fr, fq * 8), boff = lds_byte(wc * 32 + fr, fq * 8);
;     ...
;     Unit cur, nxt; int ui = 0;
;     if (!S.next(0, cur)) return;
;     f32x4 acc[2][2][4][2];
; #pragma unroll
;     for (int a = 0; a < 2; ++a)
; #pragma unroll
;         for (int b = 0; b < 2; ++b)
; #pragma unroll
;             for (int m = 0; m < 4; ++m)
; #pragma unroll
.LBB0_1538:
	s_cmp_lt_i32 s80, 15
	s_cselect_b64 s[2:3], -1, 0
	s_and_b64 s[2:3], s[2:3], s[0:1]
	s_andn2_b64 vcc, exec, s[2:3]
	s_cbranch_vccnz .LBB0_1559
	v_readfirstlane_b32 s101, v162
	s_nop 3
	s_lshr_b32 s101, s101, 6
	s_cmp_ge_u32 s101, 4
	s_cbranch_scc0 .Lsp_33164
	s_setprio 1
.Lsp_33164:
	s_cmpk_gt_i32 s92, 0x7ff
	v_readfirstlane_b32 s1, v162
	s_cbranch_scc1 .LBB0_1559
	v_lshrrev_b32_e32 v2, 1, v162
	v_and_b32_e32 v11, 24, v2
	v_lshrrev_b32_e32 v2, 5, v162
	v_and_b32_e32 v2, 4, v2
	v_bfe_u32 v3, v162, 2, 2
	s_add_u32 s33, s90, 0xc600000
	v_lshlrev_b32_e32 v0, 4, v162
	v_and_b32_e32 v1, 32, v162
	v_bfe_u32 v10, v162, 2, 4
	v_or3_b32 v2, v2, v3, v11
	v_lshrrev_b32_e32 v3, 3, v162
	s_movk_i32 s0, 0x70
	s_addc_u32 s42, s91, 0
	v_bitop3_b32 v8, v0, v1, 48 bitop3:0x6c
	v_and_b32_e32 v9, 64, v162
	v_and_or_b32 v4, v3, s0, v10
	s_movk_i32 s0, 0x60
	v_add_u32_e32 v12, 0x2000, v0
	s_add_u32 s43, s90, 0x3e00000
	v_or_b32_e32 v1, v8, v9
	v_and_or_b32 v3, v3, s0, v2
	v_lshrrev_b32_e32 v0, 7, v12
	s_movk_i32 s0, 0xf0
	s_addc_u32 s44, s91, 0
	v_lshl_or_b32 v130, v3, 12, v1
	v_and_or_b32 v3, v0, s0, v10
	s_movk_i32 s0, 0xe0
	s_ashr_i32 s46, s92, 31
	v_and_or_b32 v0, v0, s0, v2
	s_lshr_b32 s0, s46, 29
	s_add_i32 s0, s92, s0
	s_and_b32 s4, s0, -8
	s_lshr_b32 s6, s1, 6
	s_sub_i32 s4, s92, s4
	s_lshr_b32 s8, s1, 8
	s_lshl_b32 s45, s6, 10
	s_lshl_b32 s7, s4, 8
	s_ashr_i32 s0, s0, 3
	s_mul_i32 s5, s4, 0x101
	s_cmp_lt_i32 s4, 0
	s_cselect_b32 s4, s5, s7
	s_add_i32 s0, s4, s0
	s_ashr_i32 s4, s0, 31
	s_lshr_b32 s4, s4, 25
	s_add_i32 s4, s0, s4
	s_ashr_i32 s5, s4, 7
	s_lshl_b32 s7, s5, 2
	s_sub_i32 s5, 64, s7
	s_min_u32 s9, s5, 4
	s_and_b32 s4, s4, 0xffffff80
	v_lshl_or_b32 v132, v3, 12, v1
	s_sub_i32 s10, s0, s4
	v_cvt_f32_ubyte0_e32 v3, s9
	v_lshl_or_b32 v128, v4, 12, v1
	v_cvt_f32_i32_e32 v2, s10
	v_rcp_iflag_f32_e32 v4, v3
	v_lshl_or_b32 v134, v0, 12, v1
	s_ashr_i32 s0, s10, 30
	s_or_b32 s0, s0, 1
	v_mul_f32_e32 v0, v2, v4
	v_trunc_f32_e32 v0, v0
	v_fma_f32 v1, -v0, v3, v2
	v_cvt_i32_f32_e32 v0, v0
	v_cmp_ge_f32_e64 s[4:5], |v1|, v3
	s_and_b64 s[4:5], s[4:5], exec
	s_cselect_b32 s0, s0, 0
	v_readfirstlane_b32 s4, v0
	s_add_i32 s0, s4, s0
	s_mul_i32 s4, s0, s9
	s_sub_i32 s4, s10, s4
	s_sext_i32_i8 s4, s4
	s_add_i32 s28, s7, s4
	s_ashr_i32 s29, s28, 31
	s_lshl_b64 s[4:5], s[28:29], 20
	s_add_u32 s36, s33, s4
	s_addc_u32 s37, s42, s5
	s_bfe_i64 s[4:5], s[0:1], 0x80000
	s_lshl_b64 s[4:5], s[4:5], 20
	s_add_u32 s38, s43, s4
	s_addc_u32 s39, s44, s5
	s_add_i32 s29, s45, 0
	s_add_i32 m0, s29, 0x10000
	v_mov_b32_e32 v131, 0
	global_load_lds_dwordx4 v130, s[38:39]
	s_add_i32 m0, s29, 0x12000
	s_add_u32 s4, s38, 0x80000
	global_load_lds_dwordx4 v134, s[38:39]
	s_addc_u32 s5, s39, 0
	s_add_i32 m0, s29, 0x14000
	s_add_i32 s47, s29, 0x2000
	global_load_lds_dwordx4 v130, s[4:5]
	s_add_i32 m0, s29, 0x16000
	v_mov_b32_e32 v135, v131
	global_load_lds_dwordx4 v134, s[4:5]
	s_mov_b32 m0, s29
	s_add_u32 s4, s36, 0x80000
	global_load_lds_dwordx4 v128, s[36:37]
	s_mov_b32 m0, s47
	s_addc_u32 s5, s37, 0
	s_add_i32 s48, s29, 0x4000
	global_load_lds_dwordx4 v132, s[36:37]
	s_mov_b32 m0, s48
	s_add_i32 s49, s29, 0x6000
	global_load_lds_dwordx4 v128, s[4:5]
	s_mov_b32 m0, s49
	v_mov_b32_e32 v129, v131
	global_load_lds_dwordx4 v132, s[4:5]
	v_mov_b32_e32 v133, v131
	s_cmp_eq_u32 s8, 1
	s_mov_b32 s50, 0
	v_lshl_add_u64 v[6:7], s[38:39], 0, v[130:131]
	v_lshl_add_u64 v[4:5], s[38:39], 0, v[134:135]
	v_lshl_add_u64 v[0:1], s[36:37], 0, v[128:129]
	s_cselect_b64 s[4:5], -1, 0
	s_cmp_lg_u32 s8, 1
	v_lshl_add_u64 v[2:3], s[36:37], 0, v[132:133]
	s_cbranch_scc1 .LBB0_1542
	s_barrier

; #define PG8_STAGE(bufoff, gbase, voff) do { _Pragma("unroll") for (int _i = 0; _i < 2; ++_i) \
;         __builtin_amdgcn_global_load_lds((const unsigned*)((const char*)(gbase) + (voff)[_i]), (LAS unsigned*)(lds + (bufoff) + ldsw + _i * 8192), 16, 0, 0); } while (0)
; #define PG8_LDA(dst, b, h) do { _Pragma("unroll") for (int m = 0; m < 4; ++m) _Pragma("unroll") for (int k = 0; k < 2; ++k) dst[m][k] = *(const LAS bf16x8*)(lds + PG8_SA(b, h) + aoff + m * 2048 + k * 1024); } while (0)
; #define PG8_LDB(dst, b, h) do { _Pragma("unroll") for (int n = 0; n < 2; ++n) _Pragma("unroll") for (int k = 0; k < 2; ++k) dst[n][k] = *(const LAS bf16x8*)(lds + PG8_SB(b, h) + boff + n * 2048 + k * 1024); } while (0)
; #define PG8_MMA(ai, bj, At, Bt) do { __builtin_amdgcn_s_setprio(1); _Pragma("unroll") for (int m = 0; m < 4; ++m) _Pragma("unroll") for (int n = 0; n < 2; ++n) _Pragma("unroll") for (int k = 0; k < 2; ++k) \
;         acc[ai][bj][m][n] = __builtin_amdgcn_mfma_f32_16x16x32_bf16(Bt[n][k], At[m][k], acc[ai][bj][m][n], 0, 0, 0); __builtin_amdgcn_s_setprio(0); } while (0)
; #define PG8_WAIT_V(n) asm volatile("s_waitcnt vmcnt(" #n ")" ::: "memory")
; #define PG8_WAIT_L(n) asm volatile("s_waitcnt lgkmcnt(" #n ")" ::: "memory")
; #define PG8_BAR __builtin_amdgcn_s_barrier()
; template <class Epi, class Sched, bool ALIGN_EPI = false, bool SP2 = false>
; __device__ __forceinline__ void gemm_phase(LAS unsigned char* lds, const Gemm g, const Sched& S, const Epi& E) {
;     ...
;             const bool last = (t == nt - 2);
;             const char* a1 = cA + (size_t)(t + 1) * kstep;
;             const char* a2 = last ? nA : cA + (size_t)(t + 2) * kstep; const char* b2 = last ? nB : cB + (size_t)(t + 2) * kstep;
;             const char* a3 = a2 + kstep; const char* b3 = b2 + kstep;
;             if (last && has_next) S.a_ready(nxt);
;             if constexpr (SP2) {
;             PG8_LDB(B0, 0, 0); PG8_LDB(B1, 0, 1); PG8_SCHED; PG8_LDA(At, 0, 0); PG8_STAGE(PG8_SA(1, 1), a1 + hstep, voffA);
;             PG8_WAIT_V(8); PG8_WAIT_L(0); PG8_BAR; PG8_MMA(0, 0, At, B0); PG8_MMA(0, 1, At, B1); PG8_BAR; PG8_SCHED;
;             PG8_LDA(At, 0, 1); PG8_STAGE(PG8_SB(0, 0), b2, voffB); PG8_STAGE(PG8_SB(0, 1), b2 + hstep, voffB); PG8_STAGE(PG8_SA(0, 0), a2, voffA);
;             PG8_WAIT_V(8); PG8_WAIT_L(0); PG8_BAR; PG8_MMA(1, 0, At, B0); PG8_MMA(1, 1, At, B1); PG8_BAR; PG8_SCHED;
.LBB0_1552:
	ds_read_b128 v[152:155], v149
	ds_read_b128 v[156:159], v149 offset:1024
	ds_read_b128 v[164:167], v149 offset:2048
	ds_read_b128 v[170:173], v149 offset:3072
	ds_read_b128 v[174:177], v150
	ds_read_b128 v[178:181], v150 offset:1024
	ds_read_b128 v[182:185], v150 offset:2048
	ds_read_b128 v[186:189], v150 offset:3072
	s_add_u32 s38, s36, 0xfff80080
	s_addc_u32 s39, s37, -1
	s_cmp_eq_u32 s62, 28
	s_cselect_b32 s41, s31, s39
	s_cselect_b32 s40, s30, s38
	s_cselect_b32 s39, s35, s23
	s_cselect_b32 s38, s34, s21
	v_lshl_add_u64 v[144:145], s[36:37], 0, v[136:137]
	s_add_i32 m0, s29, 0xc000
	ds_read_b128 v[190:193], v151
	ds_read_b128 v[194:197], v151 offset:1024
	ds_read_b128 v[198:201], v151 offset:2048
	ds_read_b128 v[202:205], v151 offset:3072
	ds_read_b128 v[206:209], v151 offset:4096
	ds_read_b128 v[210:213], v151 offset:5120
	ds_read_b128 v[214:217], v151 offset:6144
	ds_read_b128 v[218:221], v151 offset:7168
	global_load_lds_dwordx4 v[144:145], off
	v_lshl_add_u64 v[144:145], s[36:37], 0, v[138:139]
	s_add_i32 m0, s29, 0xe000
	s_nop 0
	global_load_lds_dwordx4 v[144:145], off
	s_waitcnt vmcnt(8)
	s_waitcnt lgkmcnt(0)
	s_barrier
	s_waitcnt lgkmcnt(0)
	v_mfma_f32_16x16x32_bf16 v[124:127], v[152:155], v[190:193], v[124:127]
	v_mfma_f32_16x16x32_bf16 v[120:123], v[164:167], v[190:193], v[120:123]
	v_mfma_f32_16x16x32_bf16 v[108:111], v[152:155], v[198:201], v[108:111]
	v_mfma_f32_16x16x32_bf16 v[104:107], v[164:167], v[198:201], v[104:107]
	v_mfma_f32_16x16x32_bf16 v[92:95], v[152:155], v[206:209], v[92:95]
	v_mfma_f32_16x16x32_bf16 v[88:91], v[164:167], v[206:209], v[88:91]
	v_mfma_f32_16x16x32_bf16 v[76:79], v[152:155], v[214:217], v[76:79]
	v_mfma_f32_16x16x32_bf16 v[72:75], v[164:167], v[214:217], v[72:75]
	v_mfma_f32_16x16x32_bf16 v[124:127], v[156:159], v[194:197], v[124:127]
	v_mfma_f32_16x16x32_bf16 v[120:123], v[170:173], v[194:197], v[120:123]
	v_mfma_f32_16x16x32_bf16 v[108:111], v[156:159], v[202:205], v[108:111]
	v_mfma_f32_16x16x32_bf16 v[104:107], v[170:173], v[202:205], v[104:107]
	v_mfma_f32_16x16x32_bf16 v[92:95], v[156:159], v[210:213], v[92:95]
	v_mfma_f32_16x16x32_bf16 v[88:91], v[170:173], v[210:213], v[88:91]
	v_mfma_f32_16x16x32_bf16 v[76:79], v[156:159], v[218:221], v[76:79]
	v_mfma_f32_16x16x32_bf16 v[72:75], v[170:173], v[218:221], v[72:75]
	v_mfma_f32_16x16x32_bf16 v[116:119], v[174:177], v[190:193], v[116:119]
	v_mfma_f32_16x16x32_bf16 v[112:115], v[182:185], v[190:193], v[112:115]
	v_mfma_f32_16x16x32_bf16 v[100:103], v[174:177], v[198:201], v[100:103]
	v_mfma_f32_16x16x32_bf16 v[96:99], v[182:185], v[198:201], v[96:99]
	v_mfma_f32_16x16x32_bf16 v[84:87], v[174:177], v[206:209], v[84:87]
	v_mfma_f32_16x16x32_bf16 v[80:83], v[182:185], v[206:209], v[80:83]
	v_mfma_f32_16x16x32_bf16 v[68:71], v[174:177], v[214:217], v[68:71]
	v_mfma_f32_16x16x32_bf16 v[64:67], v[182:185], v[214:217], v[64:67]
	v_mfma_f32_16x16x32_bf16 v[116:119], v[178:181], v[194:197], v[116:119]
	v_mfma_f32_16x16x32_bf16 v[112:115], v[186:189], v[194:197], v[112:115]
	v_mfma_f32_16x16x32_bf16 v[100:103], v[178:181], v[202:205], v[100:103]
	v_mfma_f32_16x16x32_bf16 v[96:99], v[186:189], v[202:205], v[96:99]
	v_mfma_f32_16x16x32_bf16 v[84:87], v[178:181], v[210:213], v[84:87]
	v_mfma_f32_16x16x32_bf16 v[80:83], v[186:189], v[210:213], v[80:83]
	v_mfma_f32_16x16x32_bf16 v[68:71], v[178:181], v[218:221], v[68:71]
	v_mfma_f32_16x16x32_bf16 v[64:67], v[186:189], v[218:221], v[64:67]
	s_barrier
	s_add_i32 s63, s55, s45
	v_lshl_add_u64 v[144:145], s[38:39], 0, v[130:131]
	s_mov_b32 m0, s63
	ds_read_b128 v[190:193], v151 offset:16384
	ds_read_b128 v[194:197], v151 offset:17408
	ds_read_b128 v[198:201], v151 offset:18432
	ds_read_b128 v[202:205], v151 offset:19456
	ds_read_b128 v[206:209], v151 offset:20480
	ds_read_b128 v[210:213], v151 offset:21504
	ds_read_b128 v[214:217], v151 offset:22528
	ds_read_b128 v[218:221], v151 offset:23552
	global_load_lds_dwordx4 v[144:145], off
	s_add_i32 m0, s63, 0x2000
	s_add_u32 s64, s38, 0x80000
	v_lshl_add_u64 v[222:223], s[38:39], 0, v[134:135]
	s_addc_u32 s65, s39, 0
	s_add_i32 s63, s56, s45
	global_load_lds_dwordx4 v[222:223], off
	v_lshl_add_u64 v[224:225], s[64:65], 0, v[130:131]
	s_mov_b32 m0, s63
	v_lshl_add_u64 v[226:227], s[40:41], 0, v[132:133]
	global_load_lds_dwordx4 v[224:225], off
	v_lshl_add_u64 v[224:225], s[64:65], 0, v[134:135]
	s_add_i32 m0, s63, 0x2000
	s_nop 0
	global_load_lds_dwordx4 v[224:225], off
	v_lshl_add_u64 v[224:225], s[40:41], 0, v[128:129]
	s_mov_b32 m0, s29
	s_nop 0
	global_load_lds_dwordx4 v[224:225], off
	s_mov_b32 m0, s47
	s_nop 0
	global_load_lds_dwordx4 v[226:227], off
	s_waitcnt vmcnt(8)
	s_waitcnt lgkmcnt(0)
	s_barrier
; #define PG8_STAGE(bufoff, gbase, voff) do { _Pragma("unroll") for (int _i = 0; _i < 2; ++_i) \
;         __builtin_amdgcn_global_load_lds((const unsigned*)((const char*)(gbase) + (voff)[_i]), (LAS unsigned*)(lds + (bufoff) + ldsw + _i * 8192), 16, 0, 0); } while (0)
; #define PG8_LDA(dst, b, h) do { _Pragma("unroll") for (int m = 0; m < 4; ++m) _Pragma("unroll") for (int k = 0; k < 2; ++k) dst[m][k] = *(const LAS bf16x8*)(lds + PG8_SA(b, h) + aoff + m * 2048 + k * 1024); } while (0)
; #define PG8_LDB(dst, b, h) do { _Pragma("unroll") for (int n = 0; n < 2; ++n) _Pragma("unroll") for (int k = 0; k < 2; ++k) dst[n][k] = *(const LAS bf16x8*)(lds + PG8_SB(b, h) + boff + n * 2048 + k * 1024); } while (0)
; #define PG8_MMA(ai, bj, At, Bt) do { __builtin_amdgcn_s_setprio(1); _Pragma("unroll") for (int m = 0; m < 4; ++m) _Pragma("unroll") for (int n = 0; n < 2; ++n) _Pragma("unroll") for (int k = 0; k < 2; ++k) \
;         acc[ai][bj][m][n] = __builtin_amdgcn_mfma_f32_16x16x32_bf16(Bt[n][k], At[m][k], acc[ai][bj][m][n], 0, 0, 0); __builtin_amdgcn_s_setprio(0); } while (0)
; #define PG8_WAIT_V(n) asm volatile("s_waitcnt vmcnt(" #n ")" ::: "memory")
; #define PG8_WAIT_L(n) asm volatile("s_waitcnt lgkmcnt(" #n ")" ::: "memory")
; #define PG8_BAR __builtin_amdgcn_s_barrier()
; #define PG8_SCHED __builtin_amdgcn_sched_barrier(0)
; template <class Epi, class Sched, bool ALIGN_EPI = false, bool SP2 = false>
; __device__ __forceinline__ void gemm_phase(LAS unsigned char* lds, const Gemm g, const Sched& S, const Epi& E) {
;     ...
;             PG8_WAIT_V(8); PG8_WAIT_L(0); PG8_BAR; PG8_MMA(1, 0, At, B0); PG8_MMA(1, 1, At, B1); PG8_BAR; PG8_SCHED;
;             PG8_LDB(B0, 1, 0); PG8_LDB(B1, 1, 1); PG8_SCHED; PG8_LDA(At, 1, 0); PG8_STAGE(PG8_SA(0, 1), a2 + hstep, voffA);
;             PG8_WAIT_V(8); PG8_WAIT_L(0); PG8_BAR; PG8_MMA(0, 0, At, B0); PG8_MMA(0, 1, At, B1); PG8_BAR; PG8_SCHED;
	s_waitcnt lgkmcnt(0)
	v_mfma_f32_16x16x32_bf16 v[60:63], v[152:155], v[190:193], v[60:63]
	v_mfma_f32_16x16x32_bf16 v[56:59], v[164:167], v[190:193], v[56:59]
	v_mfma_f32_16x16x32_bf16 v[44:47], v[152:155], v[198:201], v[44:47]
	v_mfma_f32_16x16x32_bf16 v[40:43], v[164:167], v[198:201], v[40:43]
	v_mfma_f32_16x16x32_bf16 v[28:31], v[152:155], v[206:209], v[28:31]
	v_mfma_f32_16x16x32_bf16 v[24:27], v[164:167], v[206:209], v[24:27]
	v_mfma_f32_16x16x32_bf16 v[12:15], v[152:155], v[214:217], v[12:15]
	v_mfma_f32_16x16x32_bf16 v[8:11], v[164:167], v[214:217], v[8:11]
	v_mfma_f32_16x16x32_bf16 v[60:63], v[156:159], v[194:197], v[60:63]
	v_mfma_f32_16x16x32_bf16 v[56:59], v[170:173], v[194:197], v[56:59]
	v_mfma_f32_16x16x32_bf16 v[44:47], v[156:159], v[202:205], v[44:47]
	v_mfma_f32_16x16x32_bf16 v[40:43], v[170:173], v[202:205], v[40:43]
	v_mfma_f32_16x16x32_bf16 v[28:31], v[156:159], v[210:213], v[28:31]
	v_mfma_f32_16x16x32_bf16 v[24:27], v[170:173], v[210:213], v[24:27]
	v_mfma_f32_16x16x32_bf16 v[12:15], v[156:159], v[218:221], v[12:15]
	v_mfma_f32_16x16x32_bf16 v[8:11], v[170:173], v[218:221], v[8:11]
	v_mfma_f32_16x16x32_bf16 v[52:55], v[174:177], v[190:193], v[52:55]
	v_mfma_f32_16x16x32_bf16 v[48:51], v[182:185], v[190:193], v[48:51]
	v_mfma_f32_16x16x32_bf16 v[36:39], v[174:177], v[198:201], v[36:39]
	v_mfma_f32_16x16x32_bf16 v[32:35], v[182:185], v[198:201], v[32:35]
	v_mfma_f32_16x16x32_bf16 v[20:23], v[174:177], v[206:209], v[20:23]
	v_mfma_f32_16x16x32_bf16 v[16:19], v[182:185], v[206:209], v[16:19]
	v_mfma_f32_16x16x32_bf16 v[4:7], v[174:177], v[214:217], v[4:7]
	v_mfma_f32_16x16x32_bf16 v[0:3], v[182:185], v[214:217], v[0:3]
	v_mfma_f32_16x16x32_bf16 v[52:55], v[178:181], v[194:197], v[52:55]
	v_mfma_f32_16x16x32_bf16 v[48:51], v[186:189], v[194:197], v[48:51]
	v_mfma_f32_16x16x32_bf16 v[36:39], v[178:181], v[202:205], v[36:39]
	v_mfma_f32_16x16x32_bf16 v[32:35], v[186:189], v[202:205], v[32:35]
	v_mfma_f32_16x16x32_bf16 v[20:23], v[178:181], v[210:213], v[20:23]
	v_mfma_f32_16x16x32_bf16 v[16:19], v[186:189], v[210:213], v[16:19]
	v_mfma_f32_16x16x32_bf16 v[4:7], v[178:181], v[218:221], v[4:7]
	v_mfma_f32_16x16x32_bf16 v[0:3], v[186:189], v[218:221], v[0:3]
	s_barrier
	s_add_i32 s63, 0, 0x18000
	v_add_u32_e32 v163, s63, v147
	s_add_i32 s64, 0, 0x1c000
	ds_read_b128 v[152:155], v163
	ds_read_b128 v[156:159], v163 offset:1024
	ds_read_b128 v[164:167], v163 offset:2048
	ds_read_b128 v[170:173], v163 offset:3072
	v_add_u32_e32 v163, s64, v147
	ds_read_b128 v[174:177], v163
	ds_read_b128 v[178:181], v163 offset:1024
	ds_read_b128 v[182:185], v163 offset:2048
	ds_read_b128 v[186:189], v163 offset:3072
	s_add_u32 s40, s40, 0x80000
	s_addc_u32 s41, s41, 0
	s_mov_b32 m0, s48
	v_lshl_add_u64 v[228:229], s[40:41], 0, v[128:129]
	ds_read_b128 v[190:193], v151 offset:32768
	ds_read_b128 v[194:197], v151 offset:33792
	ds_read_b128 v[198:201], v151 offset:34816
	ds_read_b128 v[202:205], v151 offset:35840
	ds_read_b128 v[206:209], v151 offset:36864
	ds_read_b128 v[210:213], v151 offset:37888
	ds_read_b128 v[214:217], v151 offset:38912
	ds_read_b128 v[218:221], v151 offset:39936
	global_load_lds_dwordx4 v[228:229], off
	v_lshl_add_u64 v[228:229], s[40:41], 0, v[132:133]
	s_mov_b32 m0, s49
	s_nop 0
	global_load_lds_dwordx4 v[228:229], off
	s_waitcnt vmcnt(8)
	s_waitcnt lgkmcnt(0)
	s_barrier
	s_waitcnt lgkmcnt(0)
	v_mfma_f32_16x16x32_bf16 v[124:127], v[152:155], v[190:193], v[124:127]
	v_mfma_f32_16x16x32_bf16 v[120:123], v[164:167], v[190:193], v[120:123]
	v_mfma_f32_16x16x32_bf16 v[108:111], v[152:155], v[198:201], v[108:111]
	v_mfma_f32_16x16x32_bf16 v[104:107], v[164:167], v[198:201], v[104:107]
	v_mfma_f32_16x16x32_bf16 v[92:95], v[152:155], v[206:209], v[92:95]
	v_mfma_f32_16x16x32_bf16 v[88:91], v[164:167], v[206:209], v[88:91]
	v_mfma_f32_16x16x32_bf16 v[76:79], v[152:155], v[214:217], v[76:79]
	v_mfma_f32_16x16x32_bf16 v[72:75], v[164:167], v[214:217], v[72:75]
	v_mfma_f32_16x16x32_bf16 v[124:127], v[156:159], v[194:197], v[124:127]
	v_mfma_f32_16x16x32_bf16 v[120:123], v[170:173], v[194:197], v[120:123]
	v_mfma_f32_16x16x32_bf16 v[108:111], v[156:159], v[202:205], v[108:111]
	v_mfma_f32_16x16x32_bf16 v[104:107], v[170:173], v[202:205], v[104:107]
	v_mfma_f32_16x16x32_bf16 v[92:95], v[156:159], v[210:213], v[92:95]
	v_mfma_f32_16x16x32_bf16 v[88:91], v[170:173], v[210:213], v[88:91]
	v_mfma_f32_16x16x32_bf16 v[76:79], v[156:159], v[218:221], v[76:79]
	v_mfma_f32_16x16x32_bf16 v[72:75], v[170:173], v[218:221], v[72:75]
	v_mfma_f32_16x16x32_bf16 v[116:119], v[174:177], v[190:193], v[116:119]
	v_mfma_f32_16x16x32_bf16 v[112:115], v[182:185], v[190:193], v[112:115]
	v_mfma_f32_16x16x32_bf16 v[100:103], v[174:177], v[198:201], v[100:103]
	v_mfma_f32_16x16x32_bf16 v[96:99], v[182:185], v[198:201], v[96:99]
	v_mfma_f32_16x16x32_bf16 v[84:87], v[174:177], v[206:209], v[84:87]
	v_mfma_f32_16x16x32_bf16 v[80:83], v[182:185], v[206:209], v[80:83]
	v_mfma_f32_16x16x32_bf16 v[68:71], v[174:177], v[214:217], v[68:71]
	v_mfma_f32_16x16x32_bf16 v[64:67], v[182:185], v[214:217], v[64:67]
	v_mfma_f32_16x16x32_bf16 v[116:119], v[178:181], v[194:197], v[116:119]
	v_mfma_f32_16x16x32_bf16 v[112:115], v[186:189], v[194:197], v[112:115]
	v_mfma_f32_16x16x32_bf16 v[100:103], v[178:181], v[202:205], v[100:103]
	v_mfma_f32_16x16x32_bf16 v[96:99], v[186:189], v[202:205], v[96:99]
	v_mfma_f32_16x16x32_bf16 v[84:87], v[178:181], v[210:213], v[84:87]
	v_mfma_f32_16x16x32_bf16 v[80:83], v[186:189], v[210:213], v[80:83]
	v_mfma_f32_16x16x32_bf16 v[68:71], v[178:181], v[218:221], v[68:71]
	v_mfma_f32_16x16x32_bf16 v[64:67], v[186:189], v[218:221], v[64:67]
	s_barrier
; #define PG8_STAGE(bufoff, gbase, voff) do { _Pragma("unroll") for (int _i = 0; _i < 2; ++_i) \
;         __builtin_amdgcn_global_load_lds((const unsigned*)((const char*)(gbase) + (voff)[_i]), (LAS unsigned*)(lds + (bufoff) + ldsw + _i * 8192), 16, 0, 0); } while (0)
; #define PG8_LDA(dst, b, h) do { _Pragma("unroll") for (int m = 0; m < 4; ++m) _Pragma("unroll") for (int k = 0; k < 2; ++k) dst[m][k] = *(const LAS bf16x8*)(lds + PG8_SA(b, h) + aoff + m * 2048 + k * 1024); } while (0)
; #define PG8_MMA(ai, bj, At, Bt) do { __builtin_amdgcn_s_setprio(1); _Pragma("unroll") for (int m = 0; m < 4; ++m) _Pragma("unroll") for (int n = 0; n < 2; ++n) _Pragma("unroll") for (int k = 0; k < 2; ++k) \
;         acc[ai][bj][m][n] = __builtin_amdgcn_mfma_f32_16x16x32_bf16(Bt[n][k], At[m][k], acc[ai][bj][m][n], 0, 0, 0); __builtin_amdgcn_s_setprio(0); } while (0)
; #define PG8_WAIT_V(n) asm volatile("s_waitcnt vmcnt(" #n ")" ::: "memory")
; #define PG8_WAIT_L(n) asm volatile("s_waitcnt lgkmcnt(" #n ")" ::: "memory")
; #define PG8_BAR __builtin_amdgcn_s_barrier()
; #define PG8_SCHED __builtin_amdgcn_sched_barrier(0)
; template <class Epi, class Sched, bool ALIGN_EPI = false, bool SP2 = false>
; __device__ __forceinline__ void gemm_phase(LAS unsigned char* lds, const Gemm g, const Sched& S, const Epi& E) {
;     ...
;             PG8_LDA(At, 1, 1); PG8_STAGE(PG8_SB(1, 0), b3, voffB); PG8_STAGE(PG8_SB(1, 1), b3 + hstep, voffB); PG8_STAGE(PG8_SA(1, 0), a3, voffA);
;             PG8_WAIT_V(8); PG8_WAIT_L(0); PG8_BAR; PG8_MMA(1, 0, At, B0); PG8_MMA(1, 1, At, B1); PG8_BAR; PG8_SCHED;
	s_add_i32 s40, s63, s45
	v_lshl_add_u64 v[144:145], v[144:145], 0, s[6:7]
	s_mov_b32 m0, s40
	ds_read_b128 v[190:193], v151 offset:49152
	ds_read_b128 v[194:197], v151 offset:50176
	ds_read_b128 v[198:201], v151 offset:51200
	ds_read_b128 v[202:205], v151 offset:52224
	ds_read_b128 v[206:209], v151 offset:53248
	ds_read_b128 v[210:213], v151 offset:54272
	ds_read_b128 v[214:217], v151 offset:55296
	ds_read_b128 v[218:221], v151 offset:56320
	global_load_lds_dwordx4 v[144:145], off
	s_add_i32 m0, s40, 0x2000
	s_add_u32 s38, s38, 0x80080
	v_lshl_add_u64 v[144:145], v[222:223], 0, s[6:7]
	s_addc_u32 s39, s39, 0
	s_add_i32 s40, s64, s45
	global_load_lds_dwordx4 v[144:145], off
	v_lshl_add_u64 v[144:145], s[38:39], 0, v[130:131]
	s_mov_b32 m0, s40
	s_nop 0
	global_load_lds_dwordx4 v[144:145], off
	v_lshl_add_u64 v[144:145], s[38:39], 0, v[134:135]
	s_add_i32 m0, s40, 0x2000
	s_nop 0
	global_load_lds_dwordx4 v[144:145], off
	v_lshl_add_u64 v[144:145], v[224:225], 0, s[6:7]
	s_mov_b32 m0, s52
	s_nop 0
	global_load_lds_dwordx4 v[144:145], off
	v_lshl_add_u64 v[144:145], v[226:227], 0, s[6:7]
	s_mov_b32 m0, s53
	s_nop 0
	global_load_lds_dwordx4 v[144:145], off
	s_waitcnt vmcnt(8)
	s_waitcnt lgkmcnt(0)
	s_barrier
	s_waitcnt lgkmcnt(0)
	v_mfma_f32_16x16x32_bf16 v[60:63], v[152:155], v[190:193], v[60:63]
	v_mfma_f32_16x16x32_bf16 v[56:59], v[164:167], v[190:193], v[56:59]
	v_mfma_f32_16x16x32_bf16 v[44:47], v[152:155], v[198:201], v[44:47]
	v_mfma_f32_16x16x32_bf16 v[40:43], v[164:167], v[198:201], v[40:43]
	v_mfma_f32_16x16x32_bf16 v[28:31], v[152:155], v[206:209], v[28:31]
	v_mfma_f32_16x16x32_bf16 v[24:27], v[164:167], v[206:209], v[24:27]
	v_mfma_f32_16x16x32_bf16 v[12:15], v[152:155], v[214:217], v[12:15]
	v_mfma_f32_16x16x32_bf16 v[8:11], v[164:167], v[214:217], v[8:11]
	v_mfma_f32_16x16x32_bf16 v[60:63], v[156:159], v[194:197], v[60:63]
	v_mfma_f32_16x16x32_bf16 v[56:59], v[170:173], v[194:197], v[56:59]
	v_mfma_f32_16x16x32_bf16 v[44:47], v[156:159], v[202:205], v[44:47]
	v_mfma_f32_16x16x32_bf16 v[40:43], v[170:173], v[202:205], v[40:43]
	v_mfma_f32_16x16x32_bf16 v[28:31], v[156:159], v[210:213], v[28:31]
	v_mfma_f32_16x16x32_bf16 v[24:27], v[170:173], v[210:213], v[24:27]
	v_mfma_f32_16x16x32_bf16 v[12:15], v[156:159], v[218:221], v[12:15]
	v_mfma_f32_16x16x32_bf16 v[8:11], v[170:173], v[218:221], v[8:11]
	v_mfma_f32_16x16x32_bf16 v[52:55], v[174:177], v[190:193], v[52:55]
	v_mfma_f32_16x16x32_bf16 v[48:51], v[182:185], v[190:193], v[48:51]
	v_mfma_f32_16x16x32_bf16 v[36:39], v[174:177], v[198:201], v[36:39]
	v_mfma_f32_16x16x32_bf16 v[32:35], v[182:185], v[198:201], v[32:35]
	v_mfma_f32_16x16x32_bf16 v[20:23], v[174:177], v[206:209], v[20:23]
	v_mfma_f32_16x16x32_bf16 v[16:19], v[182:185], v[206:209], v[16:19]
	v_mfma_f32_16x16x32_bf16 v[4:7], v[174:177], v[214:217], v[4:7]
	v_mfma_f32_16x16x32_bf16 v[0:3], v[182:185], v[214:217], v[0:3]
	v_mfma_f32_16x16x32_bf16 v[52:55], v[178:181], v[194:197], v[52:55]
	v_mfma_f32_16x16x32_bf16 v[48:51], v[186:189], v[194:197], v[48:51]
	v_mfma_f32_16x16x32_bf16 v[36:39], v[178:181], v[202:205], v[36:39]
	v_mfma_f32_16x16x32_bf16 v[32:35], v[186:189], v[202:205], v[32:35]
	v_mfma_f32_16x16x32_bf16 v[20:23], v[178:181], v[210:213], v[20:23]
	v_mfma_f32_16x16x32_bf16 v[16:19], v[186:189], v[210:213], v[16:19]
	v_mfma_f32_16x16x32_bf16 v[4:7], v[178:181], v[218:221], v[4:7]
	v_mfma_f32_16x16x32_bf16 v[0:3], v[186:189], v[218:221], v[0:3]
	s_barrier
	s_add_i32 s62, s62, 2
	s_add_u32 s36, s36, 0x100
	s_addc_u32 s37, s37, 0
	s_add_u32 s21, s21, 0x100
	s_addc_u32 s23, s23, 0
	s_cmp_gt_u32 s62, 29
	s_cbranch_scc0 .LBB0_1552
	s_and_b64 vcc, exec, s[8:9]
	s_cbranch_vccz .LBB0_1555
	s_barrier

; __device__ __forceinline__ unsigned xb_ld(unsigned* p)              { return __hip_atomic_load(p, __ATOMIC_RELAXED, __HIP_MEMORY_SCOPE_AGENT); }
; __device__ __forceinline__ void xcd_barrier_complete(unsigned* bar, unsigned x, unsigned& nloc, unsigned& nx) {
;     const unsigned G = gridDim.x * gridDim.y * gridDim.z;
;     unsigned sum, cnt, mine, sp = 0u;
;     for (;;) {
;         sum = 0u; cnt = 0u; mine = 0u;
; #pragma unroll
;         for (unsigned j = 0; j < 16; ++j) { const unsigned c = xb_ld(&bar[XB_XCNT(j)]); sum += c; cnt += (c > 0u) ? 1u : 0u; mine = (j == x) ? c : mine; }
; __device__ __forceinline__ void xcd_barrier(const XcdBarrier& b) {
;     asm volatile("s_waitcnt vmcnt(0)" ::: "memory");
;     __syncthreads();
;     if (threadIdx.x == 0) {
;         unsigned* bar = b.bar;
;         __builtin_amdgcn_s_waitcnt(0);
;         unsigned nloc = b.st[0], nx = b.st[1];
;         if (nloc == 0u) { xcd_barrier_complete(bar, b.x, nloc, nx); b.st[0] = nloc; b.st[1] = nx; }
.LBB0_1559:
	s_setprio 0
	s_cmp_gt_i32 s81, 15
	s_cselect_b64 s[0:1], -1, 0
	s_and_b64 s[2:3], s[2:3], s[0:1]
	s_andn2_b64 vcc, exec, s[2:3]
	s_cbranch_vccnz .LBB0_1613
	s_waitcnt vmcnt(0)
	s_waitcnt vmcnt(0)
	s_barrier
	s_and_saveexec_b64 s[2:3], s[94:95]
	s_cbranch_execz .LBB0_1612
	s_add_i32 s4, 0, 0x23fc0
	v_mov_b32_e32 v0, s4
	s_waitcnt vmcnt(0) expcnt(0) lgkmcnt(0)
	ds_read_b32 v2, v0
	s_add_i32 s4, 0, 0x23fc4
	v_mov_b32_e32 v0, s4
	ds_read_b32 v0, v0
	s_waitcnt lgkmcnt(1)
	v_cmp_ne_u32_e32 vcc, 0, v2
	s_cbranch_vccnz .LBB0_1576
	v_readlane_b32 s4, v241, 0
	s_mul_i32 s33, s83, s4
	s_add_u32 s4, s90, 0x88200
	s_addc_u32 s5, s91, 0
	s_add_u32 s6, s90, 0x88400
	s_addc_u32 s7, s91, 0
	s_add_u32 s8, s90, 0x88500
	s_addc_u32 s9, s91, 0
	s_add_u32 s10, s90, 0x88600
	s_addc_u32 s11, s91, 0
	s_add_u32 s12, s90, 0x88700
	s_addc_u32 s13, s91, 0
	s_add_u32 s14, s90, 0x88800
	s_addc_u32 s15, s91, 0
	s_add_u32 s16, s90, 0x88900
	s_addc_u32 s17, s91, 0
	s_add_u32 s18, s90, 0x88a00
	s_addc_u32 s19, s91, 0
	s_add_u32 s20, s90, 0x88b00
	s_addc_u32 s21, s91, 0
	s_add_u32 s22, s90, 0x88c00
	s_addc_u32 s23, s91, 0
	s_add_u32 s24, s90, 0x88d00
	s_addc_u32 s25, s91, 0
	s_add_u32 s26, s90, 0x88e00
	s_addc_u32 s27, s91, 0
	s_add_u32 s28, s90, 0x88f00
	s_addc_u32 s29, s91, 0
	s_add_u32 s30, s90, 0x89000
	s_addc_u32 s31, s91, 0
	s_add_u32 s34, s90, 0x89100
	s_addc_u32 s35, s91, 0
	s_add_u32 s36, s90, 0x89200
	s_addc_u32 s37, s91, 0
	s_add_u32 s38, s90, 0x89300
	s_mul_i32 s33, s33, s82
	s_addc_u32 s39, s91, 0
	s_mov_b32 s46, 1
	v_mov_b32_e32 v16, 0
	s_branch .LBB0_1564
